# v24 + PREP GEMV 2-deep prefetch (unroll 2), FFN-in epilogue: 160 redundant DPP zero-init movs removed
# speedup vs baseline: 1.0237x; 1.0029x over previous
; DI float fexp2(float x) { return __builtin_amdgcn_exp2f(x); }
; DI float frcp(float x) { return __builtin_amdgcn_rcpf(x); }
; DI float dpp_ror1(float v) { return __int_as_float(__builtin_amdgcn_update_dpp(0, __float_as_int(v), 0x121, 0xf, 0xf, false)); }
; DI float dpp_ror2(float v) { return __int_as_float(__builtin_amdgcn_update_dpp(0, __float_as_int(v), 0x122, 0xf, 0xf, false)); }
;     __device__ __forceinline__ void operator()(const f32x4 (&acc)[2][2][4][2], const Unit& u, int wr, int wc, int fr, int fq) const {
;     ...
;             for (int n = 0; n < 2; ++n) {
;                 const int ch = u.pn * 128 + wc * 32 + 8 * fq + 4 * n;
;                 const f32x4 w0 = *(const f32x4*)(cw + ch), w1 = *(const f32x4*)(cw + DFF + ch), w2 = *(const f32x4*)(cw + 2 * DFF + ch), bb = *(const f32x4*)(cb + ch);
; #pragma unroll
;                 for (int ai = 0; ai < 2; ++ai) {
;                     f32x4 gp = (f32x4){0.f, 0.f, 0.f, 0.f};
; #pragma unroll
;                     for (int m = 0; m < 4; ++m) {
;                         const int row = u.pm * BM + ai * HALF + wr * 64 + m * 16 + fr;
;                         const f32x4 g = acc[ai][0][m][n], uu = acc[ai][1][m][n];
;                         f32x4 g1, g2, a;
; #pragma unroll
;                         for (int e = 0; e < 4; ++e) {
;                             const float c1 = dpp_ror1(g[e]), c2 = dpp_ror2(g[e]), p1 = dpp_ror1(gp[e]), p2 = dpp_ror2(gp[e]);
;                             g1[e] = (fr >= 1) ? c1 : p1; g2[e] = (fr >= 2) ? c2 : p2;
;                             const float z = w0[e] * g2[e] + w1[e] * g1[e] + w2[e] * g[e] + bb[e];
;                             a[e] = z * frcp(1.f + fexp2(-LOG2E * z)) * uu[e];
;                         }
.LBB0_955:
	s_and_b64 vcc, exec, s[2:3]
	s_cbranch_vccz .LBB0_954
	s_load_dwordx4 s[36:39], s[0:1], 0xe8
	v_readlane_b32 s0, v255, 28
	v_lshl_or_b32 v172, s59, 7, v192
	v_ashrrev_i32_e32 v173, 31, v172
	v_lshlrev_b64 v[142:143], 2, v[172:173]
	s_waitcnt lgkmcnt(0)
	s_add_u32 s2, s36, s0
	v_readlane_b32 s0, v255, 27
	s_addc_u32 s3, s37, s0
	v_readlane_b32 s0, v255, 30
	s_add_u32 s14, s38, s0
	v_readlane_b32 s0, v255, 29
	s_addc_u32 s15, s39, s0
	s_add_u32 s0, s66, 0x16b80000
	s_addc_u32 s1, s67, 0
	s_add_u32 s16, s2, 0x2c00
	s_addc_u32 s17, s3, 0
	s_add_u32 s34, s2, 0x5800
	s_addc_u32 s35, s3, 0
	v_lshl_add_u64 v[176:177], s[2:3], 0, v[142:143]
	v_lshl_add_u64 v[134:135], s[16:17], 0, v[142:143]
	v_lshl_add_u64 v[136:137], s[34:35], 0, v[142:143]
	v_lshl_add_u64 v[178:179], s[14:15], 0, v[142:143]
	global_load_dwordx4 v[130:133], v[176:177], off
	global_load_dwordx4 v[138:141], v[134:135], off
	s_nop 0
	global_load_dwordx4 v[134:137], v[136:137], off
	s_lshl_b32 s14, s76, 8
	global_load_dwordx4 v[142:145], v[178:179], off
	s_add_i32 s9, s14, s56
	v_mov_b32_dpp v186, v122 row_ror:1 row_mask:0xf bank_mask:0xf
	v_mov_b32_dpp v188, v122 row_ror:2 row_mask:0xf bank_mask:0xf
	v_mov_b32_dpp v187, v123 row_ror:1 row_mask:0xf bank_mask:0xf
	v_mov_b32_dpp v189, v123 row_ror:2 row_mask:0xf bank_mask:0xf
	v_mov_b32_dpp v182, v124 row_ror:1 row_mask:0xf bank_mask:0xf
	v_mov_b32_dpp v184, v124 row_ror:2 row_mask:0xf bank_mask:0xf
	v_mov_b32_dpp v183, v125 row_ror:1 row_mask:0xf bank_mask:0xf
	v_mov_b32_dpp v185, v125 row_ror:2 row_mask:0xf bank_mask:0xf
	v_or_b32_e32 v96, s9, v156
	s_and_saveexec_b64 s[2:3], s[44:45]
	s_xor_b64 s[2:3], exec, s[2:3]
	s_movk_i32 s7, 0x2000
	s_cbranch_execz .LBB0_958
	s_ashr_i32 s6, s9, 4
	v_or_b32_e32 v96, s6, v156
	v_mov_b64_e32 v[180:181], s[0:1]
	v_mad_i64_i32 v[180:181], s[38:39], v96, s83, v[180:181]
	s_ashr_i32 s36, s9, 6
	v_lshl_add_u64 v[180:181], v[172:173], 1, v[180:181]
	s_ashr_i32 s37, s36, 31
	v_add_co_u32_e32 v180, vcc, s7, v180
	v_cvt_pk_bf16_f32 v174, v122, v123
	v_cvt_pk_bf16_f32 v175, v124, v125
	v_addc_co_u32_e32 v181, vcc, 0, v181, vcc
	s_lshl_b64 s[36:37], s[36:37], 1
	global_store_dwordx2 v[180:181], v[174:175], off offset:3072
	v_cvt_pk_bf16_f32 v180, v126, v127
	v_cvt_pk_bf16_f32 v181, v128, v129
	v_mov_b32_e32 v147, s37
	v_or_b32_e32 v96, s36, v156
	v_or_b32_e32 v174, s9, v156

; DI unsigned pk2(float lo, float hi) { f32x2 v = {lo, hi}; bf16x2_t b = __builtin_convertvector(v, bf16x2_t); return __builtin_bit_cast(unsigned, b); }
; DI float fexp2(float x) { return __builtin_amdgcn_exp2f(x); }
; DI float frcp(float x) { return __builtin_amdgcn_rcpf(x); }
; DI float dpp_ror1(float v) { return __int_as_float(__builtin_amdgcn_update_dpp(0, __float_as_int(v), 0x121, 0xf, 0xf, false)); }
; DI float dpp_ror2(float v) { return __int_as_float(__builtin_amdgcn_update_dpp(0, __float_as_int(v), 0x122, 0xf, 0xf, false)); }
;     __device__ __forceinline__ void operator()(const f32x4 (&acc)[2][2][4][2], const Unit& u, int wr, int wc, int fr, int fq) const {
;     ...
;                         const int row = u.pm * BM + ai * HALF + wr * 64 + m * 16 + fr;
;                         const f32x4 g = acc[ai][0][m][n], uu = acc[ai][1][m][n];
;                         f32x4 g1, g2, a;
; #pragma unroll
;                         for (int e = 0; e < 4; ++e) {
;                             const float c1 = dpp_ror1(g[e]), c2 = dpp_ror2(g[e]), p1 = dpp_ror1(gp[e]), p2 = dpp_ror2(gp[e]);
;                             g1[e] = (fr >= 1) ? c1 : p1; g2[e] = (fr >= 2) ? c2 : p2;
;                             const float z = w0[e] * g2[e] + w1[e] * g1[e] + w2[e] * g[e] + bb[e];
;                             a[e] = z * frcp(1.f + fexp2(-LOG2E * z)) * uu[e];
;                         }
;                         if (m > 0 || fr >= 2) { u32x2 w; w.x = pk2(a[0], a[1]); w.y = pk2(a[2], a[3]); *(u32x2*)(A2 + (size_t)row * DFF + ch) = w; }
;                         else { u32x2 w; w.x = pk2(g[0], g[1]); w.y = pk2(g[2], g[3]); *(u32x2*)(SBG + ((size_t)(row >> 6) * 4 + 2 + fr) * DFF + ch) = w;
;                                u32x2 w2_; w2_.x = pk2(uu[0], uu[1]); w2_.y = pk2(uu[2], uu[3]); *(u32x2*)(SBU + ((size_t)(row >> 6) * 2 + fr) * DFF + ch) = w2_; }
;                         if (m == 3 && fr >= 14) { u32x2 w; w.x = pk2(g[0], g[1]); w.y = pk2(g[2], g[3]); *(u32x2*)(SBG + ((size_t)(row >> 6) * 4 + (fr - 14)) * DFF + ch) = w;
;                             const int s = row & 2047; if (s >= SEQ - 2) *(f32x4*)(outp + O_FP + (size_t)l * NBP * 2 * DFF + ((size_t)(row >> 11) * 2 + (s - (SEQ - 2))) * DFF + ch) = g; }
;                         gp = g;
.LBB0_960:
	s_or_b64 exec, exec, s[2:3]
	v_lshlrev_b64 v[182:183], 1, v[172:173]
	v_lshl_add_u64 v[184:185], s[66:67], 0, v[190:191]
	v_lshl_add_u64 v[128:129], s[30:31], 0, v[182:183]
	v_lshl_add_u64 v[126:127], s[0:1], 0, v[182:183]
	v_lshl_add_u64 v[182:183], v[184:185], 0, v[182:183]
	v_mad_u64_u32 v[182:183], s[2:3], v96, s83, v[182:183]
	v_mov_b32_e32 v96, v183
	v_mad_u64_u32 v[184:185], s[2:3], v147, s83, v[96:97]
	v_mov_b32_e32 v183, v184
	global_store_dwordx2 v[182:183], v[180:181], off
	v_mov_b32_dpp v147, v118 row_ror:2 row_mask:0xf bank_mask:0xf
	v_mov_b32_dpp v167, v122 row_ror:1 row_mask:0xf bank_mask:0xf
	v_mov_b32_dpp v175, v122 row_ror:2 row_mask:0xf bank_mask:0xf
	v_mov_b32_dpp v181, v119 row_ror:2 row_mask:0xf bank_mask:0xf
	v_mov_b32_dpp v182, v123 row_ror:2 row_mask:0xf bank_mask:0xf
	v_mov_b32_dpp v96, v118 row_ror:1 row_mask:0xf bank_mask:0xf
	v_mov_b32_dpp v180, v119 row_ror:1 row_mask:0xf bank_mask:0xf
	v_mov_b32_dpp v122, v123 row_ror:1 row_mask:0xf bank_mask:0xf
	v_mov_b32_dpp v185, v124 row_ror:1 row_mask:0xf bank_mask:0xf
	v_mov_b32_dpp v186, v124 row_ror:2 row_mask:0xf bank_mask:0xf
	v_mov_b32_dpp v189, v125 row_ror:1 row_mask:0xf bank_mask:0xf
	v_mov_b32_dpp v190, v125 row_ror:2 row_mask:0xf bank_mask:0xf
	v_cndmask_b32_e64 v125, v182, v181, s[46:47]
	v_cndmask_b32_e64 v124, v175, v147, s[46:47]
	v_cndmask_b32_e64 v123, v180, v122, s[42:43]
	v_cndmask_b32_e64 v122, v96, v167, s[42:43]
	s_waitcnt vmcnt(0)
	v_pk_mul_f32 v[124:125], v[130:131], v[124:125]
	v_pk_fma_f32 v[122:123], v[138:139], v[122:123], v[124:125]
	v_pk_fma_f32 v[118:119], v[118:119], v[134:135], v[122:123]
	v_pk_add_f32 v[118:119], v[142:143], v[118:119]
	v_mov_b32_dpp v184, v120 row_ror:2 row_mask:0xf bank_mask:0xf
	v_mul_f32_e32 v122, 0xbfb8aa3b, v118
	v_mul_f32_e32 v123, 0xbfb8aa3b, v119
	v_exp_f32_e32 v122, v122
	v_exp_f32_e32 v123, v123
	v_mov_b32_dpp v188, v121 row_ror:2 row_mask:0xf bank_mask:0xf
	v_add_f32_e32 v122, 1.0, v122
	v_add_f32_e32 v123, 1.0, v123
	v_rcp_f32_e32 v122, v122
	v_rcp_f32_e32 v123, v123
	v_mov_b32_dpp v183, v120 row_ror:1 row_mask:0xf bank_mask:0xf
	v_mov_b32_dpp v187, v121 row_ror:1 row_mask:0xf bank_mask:0xf
	v_pk_mul_f32 v[118:119], v[118:119], v[122:123]
	v_cndmask_b32_e64 v123, v190, v188, s[46:47]
	v_cndmask_b32_e64 v122, v186, v184, s[46:47]
	v_pk_mul_f32 v[118:119], v[114:115], v[118:119]
	v_cndmask_b32_e64 v115, v187, v189, s[42:43]
	v_cndmask_b32_e64 v114, v183, v185, s[42:43]
	v_pk_mul_f32 v[122:123], v[132:133], v[122:123]
	v_cvt_pk_bf16_f32 v118, v118, v119
	v_pk_fma_f32 v[114:115], v[140:141], v[114:115], v[122:123]
	v_pk_fma_f32 v[114:115], v[120:121], v[136:137], v[114:115]
	v_pk_add_f32 v[114:115], v[144:145], v[114:115]
	v_mov_b32_dpp v123, v111 row_ror:2 row_mask:0xf bank_mask:0xf
	v_mul_f32_e32 v120, 0xbfb8aa3b, v114
	v_mul_f32_e32 v121, 0xbfb8aa3b, v115
	v_exp_f32_e32 v120, v120
	v_exp_f32_e32 v121, v121
	v_mov_b32_dpp v122, v111 row_ror:1 row_mask:0xf bank_mask:0xf
	v_add_f32_e32 v120, 1.0, v120
	v_add_f32_e32 v121, 1.0, v121
	v_rcp_f32_e32 v120, v120
	v_rcp_f32_e32 v121, v121
	v_mov_b32_dpp v125, v112 row_ror:2 row_mask:0xf bank_mask:0xf
	v_pk_mul_f32 v[114:115], v[114:115], v[120:121]
	v_pk_mul_f32 v[116:117], v[116:117], v[114:115]
	v_or_b32_e32 v114, 16, v174
	v_cvt_pk_bf16_f32 v119, v116, v117
	v_mad_i64_i32 v[116:117], s[2:3], v114, s83, v[128:129]
	v_mov_b32_dpp v121, v110 row_ror:2 row_mask:0xf bank_mask:0xf
	global_store_dwordx2 v[116:117], v[118:119], off
	v_mov_b32_dpp v120, v110 row_ror:1 row_mask:0xf bank_mask:0xf
	v_cndmask_b32_e64 v119, v181, v123, s[46:47]
	v_cndmask_b32_e64 v118, v147, v121, s[46:47]
	v_cndmask_b32_e64 v117, v122, v180, s[42:43]
	v_cndmask_b32_e64 v116, v120, v96, s[42:43]
	v_pk_mul_f32 v[118:119], v[130:131], v[118:119]
	v_mov_b32_dpp v175, v113 row_ror:2 row_mask:0xf bank_mask:0xf
	v_pk_fma_f32 v[116:117], v[138:139], v[116:117], v[118:119]
	v_mov_b32_dpp v124, v112 row_ror:1 row_mask:0xf bank_mask:0xf
	v_pk_fma_f32 v[110:111], v[110:111], v[134:135], v[116:117]
	v_mov_b32_dpp v167, v113 row_ror:1 row_mask:0xf bank_mask:0xf
	v_pk_add_f32 v[110:111], v[142:143], v[110:111]
	v_or_b32_e32 v115, 48, v174
	v_mul_f32_e32 v96, 0xbfb8aa3b, v110
	v_exp_f32_e32 v96, v96
	s_nop 0
	v_add_f32_e32 v96, 1.0, v96
	v_rcp_f32_e32 v116, v96
	v_mul_f32_e32 v96, 0xbfb8aa3b, v111
	v_exp_f32_e32 v96, v96
	s_nop 0
	v_add_f32_e32 v96, 1.0, v96
	v_rcp_f32_e32 v117, v96
	s_nop 0
	v_pk_mul_f32 v[110:111], v[110:111], v[116:117]
	v_cndmask_b32_e64 v117, v188, v175, s[46:47]
	v_cndmask_b32_e64 v116, v184, v125, s[46:47]
	v_pk_mul_f32 v[106:107], v[106:107], v[110:111]
	v_cndmask_b32_e64 v111, v167, v187, s[42:43]
	v_cndmask_b32_e64 v110, v124, v183, s[42:43]
	v_pk_mul_f32 v[116:117], v[132:133], v[116:117]
	v_cvt_pk_bf16_f32 v106, v106, v107
	v_pk_fma_f32 v[110:111], v[140:141], v[110:111], v[116:117]
	v_pk_fma_f32 v[110:111], v[112:113], v[136:137], v[110:111]
	s_nop 0
	v_pk_add_f32 v[110:111], v[144:145], v[110:111]
; DI unsigned pk2(float lo, float hi) { f32x2 v = {lo, hi}; bf16x2_t b = __builtin_convertvector(v, bf16x2_t); return __builtin_bit_cast(unsigned, b); }
; DI float fexp2(float x) { return __builtin_amdgcn_exp2f(x); }
; DI float frcp(float x) { return __builtin_amdgcn_rcpf(x); }
; DI float dpp_ror1(float v) { return __int_as_float(__builtin_amdgcn_update_dpp(0, __float_as_int(v), 0x121, 0xf, 0xf, false)); }
; DI float dpp_ror2(float v) { return __int_as_float(__builtin_amdgcn_update_dpp(0, __float_as_int(v), 0x122, 0xf, 0xf, false)); }
;     __device__ __forceinline__ void operator()(const f32x4 (&acc)[2][2][4][2], const Unit& u, int wr, int wc, int fr, int fq) const {
;     ...
;                         const int row = u.pm * BM + ai * HALF + wr * 64 + m * 16 + fr;
;                         const f32x4 g = acc[ai][0][m][n], uu = acc[ai][1][m][n];
;                         f32x4 g1, g2, a;
; #pragma unroll
;                         for (int e = 0; e < 4; ++e) {
;                             const float c1 = dpp_ror1(g[e]), c2 = dpp_ror2(g[e]), p1 = dpp_ror1(gp[e]), p2 = dpp_ror2(gp[e]);
;                             g1[e] = (fr >= 1) ? c1 : p1; g2[e] = (fr >= 2) ? c2 : p2;
;                             const float z = w0[e] * g2[e] + w1[e] * g1[e] + w2[e] * g[e] + bb[e];
;                             a[e] = z * frcp(1.f + fexp2(-LOG2E * z)) * uu[e];
;                         }
;                         if (m > 0 || fr >= 2) { u32x2 w; w.x = pk2(a[0], a[1]); w.y = pk2(a[2], a[3]); *(u32x2*)(A2 + (size_t)row * DFF + ch) = w; }
;                         else { u32x2 w; w.x = pk2(g[0], g[1]); w.y = pk2(g[2], g[3]); *(u32x2*)(SBG + ((size_t)(row >> 6) * 4 + 2 + fr) * DFF + ch) = w;
;                                u32x2 w2_; w2_.x = pk2(uu[0], uu[1]); w2_.y = pk2(uu[2], uu[3]); *(u32x2*)(SBU + ((size_t)(row >> 6) * 2 + fr) * DFF + ch) = w2_; }
;                         if (m == 3 && fr >= 14) { u32x2 w; w.x = pk2(g[0], g[1]); w.y = pk2(g[2], g[3]); *(u32x2*)(SBG + ((size_t)(row >> 6) * 4 + (fr - 14)) * DFF + ch) = w;
;                             const int s = row & 2047; if (s >= SEQ - 2) *(f32x4*)(outp + O_FP + (size_t)l * NBP * 2 * DFF + ((size_t)(row >> 11) * 2 + (s - (SEQ - 2))) * DFF + ch) = g; }
;                         gp = g;
	v_mov_b32_dpp v116, v101 row_ror:2 row_mask:0xf bank_mask:0xf
	v_mul_f32_e32 v96, 0xbfb8aa3b, v110
	v_exp_f32_e32 v96, v96
	s_nop 0
	v_add_f32_e32 v96, 1.0, v96
	v_rcp_f32_e32 v112, v96
	v_mul_f32_e32 v96, 0xbfb8aa3b, v111
	v_exp_f32_e32 v96, v96
	s_nop 0
	v_add_f32_e32 v96, 1.0, v96
	v_rcp_f32_e32 v113, v96
	s_nop 0
	v_pk_mul_f32 v[110:111], v[110:111], v[112:113]
	s_nop 0
	v_pk_mul_f32 v[108:109], v[108:109], v[110:111]
	v_or_b32_e32 v113, 32, v174
	v_cvt_pk_bf16_f32 v107, v108, v109
	v_mad_i64_i32 v[108:109], s[2:3], v113, s83, v[128:129]
	global_store_dwordx2 v[108:109], v[106:107], off
	v_mov_b32_dpp v108, v98 row_ror:2 row_mask:0xf bank_mask:0xf
	v_mov_b32_dpp v109, v99 row_ror:2 row_mask:0xf bank_mask:0xf
	v_mov_b32_dpp v96, v98 row_ror:1 row_mask:0xf bank_mask:0xf
	v_mov_b32_dpp v106, v99 row_ror:1 row_mask:0xf bank_mask:0xf
	v_cndmask_b32_e64 v109, v123, v109, s[46:47]
	v_cndmask_b32_e64 v108, v121, v108, s[46:47]
	v_cndmask_b32_e64 v107, v106, v122, s[42:43]
	v_cndmask_b32_e64 v106, v96, v120, s[42:43]
	v_pk_mul_f32 v[108:109], v[130:131], v[108:109]
	v_pk_fma_f32 v[106:107], v[138:139], v[106:107], v[108:109]
	v_pk_fma_f32 v[106:107], v[98:99], v[134:135], v[106:107]
	v_mov_b32_dpp v111, v100 row_ror:2 row_mask:0xf bank_mask:0xf
	v_pk_add_f32 v[106:107], v[142:143], v[106:107]
	v_mul_f32_e32 v96, 0xbfb8aa3b, v106
	v_exp_f32_e32 v96, v96
	v_mov_b32_dpp v110, v100 row_ror:1 row_mask:0xf bank_mask:0xf
	v_mov_b32_dpp v112, v101 row_ror:1 row_mask:0xf bank_mask:0xf
	v_add_f32_e32 v96, 1.0, v96
	v_rcp_f32_e32 v108, v96
	v_mul_f32_e32 v96, 0xbfb8aa3b, v107
	v_exp_f32_e32 v96, v96
	s_nop 0
	v_add_f32_e32 v96, 1.0, v96
	v_rcp_f32_e32 v109, v96
	s_nop 0
	v_pk_mul_f32 v[106:107], v[106:107], v[108:109]
	v_cndmask_b32_e64 v109, v175, v116, s[46:47]
	v_cndmask_b32_e64 v108, v125, v111, s[46:47]
	v_pk_mul_f32 v[102:103], v[102:103], v[106:107]
	v_cndmask_b32_e64 v107, v112, v167, s[42:43]
	v_cndmask_b32_e64 v106, v110, v124, s[42:43]
	v_pk_mul_f32 v[108:109], v[132:133], v[108:109]
	v_cvt_pk_bf16_f32 v102, v102, v103
	v_pk_fma_f32 v[106:107], v[140:141], v[106:107], v[108:109]
	v_and_b32_e32 v112, 0x7ff, v115
	v_pk_fma_f32 v[106:107], v[100:101], v[136:137], v[106:107]
	s_nop 0
	v_pk_add_f32 v[106:107], v[144:145], v[106:107]
	s_nop 0
	v_mul_f32_e32 v96, 0xbfb8aa3b, v106
	v_exp_f32_e32 v96, v96
	s_nop 0
	v_add_f32_e32 v96, 1.0, v96
	v_rcp_f32_e32 v108, v96
	v_mul_f32_e32 v96, 0xbfb8aa3b, v107
	v_exp_f32_e32 v96, v96
	s_nop 0
	v_add_f32_e32 v96, 1.0, v96
	v_rcp_f32_e32 v109, v96
	s_nop 0
	v_pk_mul_f32 v[106:107], v[106:107], v[108:109]
	s_nop 0
	v_pk_mul_f32 v[104:105], v[104:105], v[106:107]
	s_nop 0
	v_cvt_pk_bf16_f32 v103, v104, v105
	v_mad_i64_i32 v[104:105], s[2:3], v115, s83, v[128:129]
	global_store_dwordx2 v[104:105], v[102:103], off
	s_and_saveexec_b64 s[2:3], s[48:49]
	s_cbranch_execz .LBB0_963
	s_ashr_i32 s36, s9, 6
	s_ashr_i32 s37, s36, 31
	v_lshl_add_u64 v[104:105], s[36:37], 2, v[160:161]
	v_mad_u64_u32 v[106:107], s[36:37], v104, s83, v[126:127]
	s_movk_i32 s6, 0x7fd
	v_cvt_pk_bf16_f32 v102, v98, v99
	v_cvt_pk_bf16_f32 v103, v100, v101
	v_mad_i32_i24 v107, v105, s83, v107
	v_cmp_lt_u32_e32 vcc, s6, v112
	global_store_dwordx2 v[106:107], v[102:103], off
	s_and_b64 exec, exec, vcc
	s_cbranch_execz .LBB0_963
	s_ashr_i32 s36, s9, 11
	s_ashr_i32 s37, s36, 31
	v_add_u32_e32 v96, 0xfffff802, v112
	v_lshl_add_u64 v[102:103], s[36:37], 1, v[96:97]
	v_mov_b64_e32 v[104:105], s[28:29]
	s_movk_i32 s6, 0x2c00
	v_mad_u64_u32 v[104:105], s[36:37], v102, s6, v[104:105]
	v_mad_i32_i24 v105, v103, s6, v105
	v_lshl_add_u64 v[102:103], v[172:173], 2, v[104:105]
	global_store_dwordx4 v[102:103], v[98:101], off
.LBB0_963:
	s_or_b64 exec, exec, s[2:3]
	v_readlane_b32 s2, v255, 22
	s_add_i32 s14, s14, s2
	v_mov_b32_dpp v106, v88 row_ror:1 row_mask:0xf bank_mask:0xf
	v_mov_b32_dpp v108, v88 row_ror:2 row_mask:0xf bank_mask:0xf
	v_mov_b32_dpp v107, v89 row_ror:1 row_mask:0xf bank_mask:0xf
	v_mov_b32_dpp v109, v89 row_ror:2 row_mask:0xf bank_mask:0xf
	v_mov_b32_dpp v102, v90 row_ror:1 row_mask:0xf bank_mask:0xf
	v_mov_b32_dpp v104, v90 row_ror:2 row_mask:0xf bank_mask:0xf
	v_mov_b32_dpp v103, v91 row_ror:1 row_mask:0xf bank_mask:0xf
	v_mov_b32_dpp v105, v91 row_ror:2 row_mask:0xf bank_mask:0xf
	v_or_b32_e32 v96, s14, v156
	s_and_saveexec_b64 s[2:3], s[44:45]
	s_xor_b64 s[2:3], exec, s[2:3]
	s_cbranch_execz .LBB0_965
	s_ashr_i32 s6, s14, 4
	v_or_b32_e32 v96, s6, v156
	v_mov_b64_e32 v[100:101], s[0:1]
	v_mad_i64_i32 v[100:101], s[38:39], v96, s83, v[100:101]
	s_ashr_i32 s36, s14, 6
	v_lshl_add_u64 v[100:101], v[172:173], 1, v[100:101]
	s_ashr_i32 s37, s36, 31
	v_add_co_u32_e32 v100, vcc, s7, v100
	v_cvt_pk_bf16_f32 v98, v88, v89
	v_cvt_pk_bf16_f32 v99, v90, v91
	v_addc_co_u32_e32 v101, vcc, 0, v101, vcc
	s_lshl_b64 s[36:37], s[36:37], 1
	global_store_dwordx2 v[100:101], v[98:99], off offset:3072
	v_cvt_pk_bf16_f32 v100, v92, v93
	v_cvt_pk_bf16_f32 v101, v94, v95
	v_mov_b32_e32 v99, s37
	v_or_b32_e32 v96, s36, v156
	v_or_b32_e32 v98, s14, v156

; DI unsigned pk2(float lo, float hi) { f32x2 v = {lo, hi}; bf16x2_t b = __builtin_convertvector(v, bf16x2_t); return __builtin_bit_cast(unsigned, b); }
; DI float fexp2(float x) { return __builtin_amdgcn_exp2f(x); }
; DI float frcp(float x) { return __builtin_amdgcn_rcpf(x); }
; DI float dpp_ror1(float v) { return __int_as_float(__builtin_amdgcn_update_dpp(0, __float_as_int(v), 0x121, 0xf, 0xf, false)); }
; DI float dpp_ror2(float v) { return __int_as_float(__builtin_amdgcn_update_dpp(0, __float_as_int(v), 0x122, 0xf, 0xf, false)); }
;     __device__ __forceinline__ void operator()(const f32x4 (&acc)[2][2][4][2], const Unit& u, int wr, int wc, int fr, int fq) const {
;     ...
;                         const int row = u.pm * BM + ai * HALF + wr * 64 + m * 16 + fr;
;                         const f32x4 g = acc[ai][0][m][n], uu = acc[ai][1][m][n];
;                         f32x4 g1, g2, a;
; #pragma unroll
;                         for (int e = 0; e < 4; ++e) {
;                             const float c1 = dpp_ror1(g[e]), c2 = dpp_ror2(g[e]), p1 = dpp_ror1(gp[e]), p2 = dpp_ror2(gp[e]);
;                             g1[e] = (fr >= 1) ? c1 : p1; g2[e] = (fr >= 2) ? c2 : p2;
;                             const float z = w0[e] * g2[e] + w1[e] * g1[e] + w2[e] * g[e] + bb[e];
;                             a[e] = z * frcp(1.f + fexp2(-LOG2E * z)) * uu[e];
;                         }
;                         if (m > 0 || fr >= 2) { u32x2 w; w.x = pk2(a[0], a[1]); w.y = pk2(a[2], a[3]); *(u32x2*)(A2 + (size_t)row * DFF + ch) = w; }
;                         else { u32x2 w; w.x = pk2(g[0], g[1]); w.y = pk2(g[2], g[3]); *(u32x2*)(SBG + ((size_t)(row >> 6) * 4 + 2 + fr) * DFF + ch) = w;
;                                u32x2 w2_; w2_.x = pk2(uu[0], uu[1]); w2_.y = pk2(uu[2], uu[3]); *(u32x2*)(SBU + ((size_t)(row >> 6) * 2 + fr) * DFF + ch) = w2_; }
;                         if (m == 3 && fr >= 14) { u32x2 w; w.x = pk2(g[0], g[1]); w.y = pk2(g[2], g[3]); *(u32x2*)(SBG + ((size_t)(row >> 6) * 4 + (fr - 14)) * DFF + ch) = w;
;                             const int s = row & 2047; if (s >= SEQ - 2) *(f32x4*)(outp + O_FP + (size_t)l * NBP * 2 * DFF + ((size_t)(row >> 11) * 2 + (s - (SEQ - 2))) * DFF + ch) = g; }
;                         gp = g;
.LBB0_967:
	s_or_b64 exec, exec, s[2:3]
	v_lshl_add_u64 v[92:93], s[66:67], 0, v[110:111]
	v_lshl_add_u64 v[92:93], v[172:173], 1, v[92:93]
	v_mad_u64_u32 v[92:93], s[2:3], v96, s83, v[92:93]
	v_mov_b32_e32 v94, v93
	v_mad_u64_u32 v[94:95], s[2:3], v99, s83, v[94:95]
	v_mov_b32_e32 v93, v94
	global_store_dwordx2 v[92:93], v[100:101], off
	v_mov_b32_dpp v93, v84 row_ror:2 row_mask:0xf bank_mask:0xf
	v_mov_b32_dpp v94, v88 row_ror:1 row_mask:0xf bank_mask:0xf
	v_mov_b32_dpp v95, v88 row_ror:2 row_mask:0xf bank_mask:0xf
	v_mov_b32_dpp v100, v85 row_ror:2 row_mask:0xf bank_mask:0xf
	v_mov_b32_dpp v99, v89 row_ror:2 row_mask:0xf bank_mask:0xf
	v_mov_b32_dpp v92, v84 row_ror:1 row_mask:0xf bank_mask:0xf
	v_mov_b32_dpp v96, v85 row_ror:1 row_mask:0xf bank_mask:0xf
	v_mov_b32_dpp v88, v89 row_ror:1 row_mask:0xf bank_mask:0xf
	v_mov_b32_dpp v103, v90 row_ror:1 row_mask:0xf bank_mask:0xf
	v_mov_b32_dpp v104, v90 row_ror:2 row_mask:0xf bank_mask:0xf
	v_mov_b32_dpp v107, v91 row_ror:1 row_mask:0xf bank_mask:0xf
	v_mov_b32_dpp v108, v91 row_ror:2 row_mask:0xf bank_mask:0xf
	v_cndmask_b32_e64 v91, v99, v100, s[46:47]
	v_cndmask_b32_e64 v90, v95, v93, s[46:47]
	v_cndmask_b32_e64 v89, v96, v88, s[42:43]
	v_cndmask_b32_e64 v88, v92, v94, s[42:43]
	v_pk_mul_f32 v[90:91], v[130:131], v[90:91]
	v_pk_fma_f32 v[88:89], v[138:139], v[88:89], v[90:91]
	v_pk_fma_f32 v[84:85], v[84:85], v[134:135], v[88:89]
	v_pk_add_f32 v[84:85], v[142:143], v[84:85]
	v_mov_b32_dpp v102, v86 row_ror:2 row_mask:0xf bank_mask:0xf
	v_mul_f32_e32 v88, 0xbfb8aa3b, v84
	v_mul_f32_e32 v89, 0xbfb8aa3b, v85
	v_exp_f32_e32 v88, v88
	v_exp_f32_e32 v89, v89
	v_mov_b32_dpp v106, v87 row_ror:2 row_mask:0xf bank_mask:0xf
	v_add_f32_e32 v88, 1.0, v88
	v_add_f32_e32 v89, 1.0, v89
	v_rcp_f32_e32 v88, v88
	v_rcp_f32_e32 v89, v89
	v_mov_b32_dpp v101, v86 row_ror:1 row_mask:0xf bank_mask:0xf
	v_mov_b32_dpp v105, v87 row_ror:1 row_mask:0xf bank_mask:0xf
	v_or_b32_e32 v99, 16, v98
	v_pk_mul_f32 v[84:85], v[84:85], v[88:89]
	v_cndmask_b32_e64 v89, v108, v106, s[46:47]
	v_cndmask_b32_e64 v88, v104, v102, s[46:47]
	v_pk_mul_f32 v[80:81], v[80:81], v[84:85]
	v_cndmask_b32_e64 v85, v105, v107, s[42:43]
	v_cndmask_b32_e64 v84, v101, v103, s[42:43]
	v_pk_mul_f32 v[88:89], v[132:133], v[88:89]
	v_cvt_pk_bf16_f32 v80, v80, v81
	v_pk_fma_f32 v[84:85], v[140:141], v[84:85], v[88:89]
	v_pk_fma_f32 v[84:85], v[86:87], v[136:137], v[84:85]
	v_pk_add_f32 v[84:85], v[144:145], v[84:85]
	v_mul_f32_e32 v86, 0xbfb8aa3b, v84
	v_mul_f32_e32 v87, 0xbfb8aa3b, v85
	v_exp_f32_e32 v86, v86
	v_exp_f32_e32 v87, v87
	v_mov_b32_dpp v89, v78 row_ror:2 row_mask:0xf bank_mask:0xf
	v_add_f32_e32 v86, 1.0, v86
	v_add_f32_e32 v87, 1.0, v87
	v_rcp_f32_e32 v86, v86
	v_rcp_f32_e32 v87, v87
	v_mov_b32_dpp v91, v79 row_ror:2 row_mask:0xf bank_mask:0xf
	v_mov_b32_dpp v88, v78 row_ror:1 row_mask:0xf bank_mask:0xf
	v_mov_b32_dpp v90, v79 row_ror:1 row_mask:0xf bank_mask:0xf
	v_pk_mul_f32 v[84:85], v[84:85], v[86:87]
	v_pk_mul_f32 v[82:83], v[82:83], v[84:85]
	v_cvt_pk_bf16_f32 v81, v82, v83
	v_mad_i64_i32 v[82:83], s[2:3], v99, s83, v[128:129]
	v_mov_b32_dpp v85, v76 row_ror:2 row_mask:0xf bank_mask:0xf
	v_mov_b32_dpp v87, v77 row_ror:2 row_mask:0xf bank_mask:0xf
	global_store_dwordx2 v[82:83], v[80:81], off
	v_mov_b32_dpp v84, v76 row_ror:1 row_mask:0xf bank_mask:0xf
	v_mov_b32_dpp v86, v77 row_ror:1 row_mask:0xf bank_mask:0xf
	v_cndmask_b32_e64 v83, v100, v87, s[46:47]
	v_cndmask_b32_e64 v82, v93, v85, s[46:47]
	v_cndmask_b32_e64 v81, v86, v96, s[42:43]
	v_cndmask_b32_e64 v80, v84, v92, s[42:43]
	v_pk_mul_f32 v[82:83], v[130:131], v[82:83]
	v_or_b32_e32 v100, 32, v98
	v_pk_fma_f32 v[80:81], v[138:139], v[80:81], v[82:83]
	s_nop 0
	v_pk_fma_f32 v[76:77], v[76:77], v[134:135], v[80:81]
	s_nop 0
	v_pk_add_f32 v[76:77], v[142:143], v[76:77]
	s_nop 0
	v_mul_f32_e32 v80, 0xbfb8aa3b, v76
	v_mul_f32_e32 v81, 0xbfb8aa3b, v77
	v_exp_f32_e32 v80, v80
	v_exp_f32_e32 v81, v81
	v_add_f32_e32 v80, 1.0, v80
	v_add_f32_e32 v81, 1.0, v81
	v_rcp_f32_e32 v80, v80
	v_rcp_f32_e32 v81, v81
	s_nop 0
	v_pk_mul_f32 v[76:77], v[76:77], v[80:81]
	v_cndmask_b32_e64 v81, v106, v91, s[46:47]
	v_cndmask_b32_e64 v80, v102, v89, s[46:47]
	v_pk_mul_f32 v[72:73], v[72:73], v[76:77]
	v_cndmask_b32_e64 v77, v90, v105, s[42:43]
	v_cndmask_b32_e64 v76, v88, v101, s[42:43]
	v_pk_mul_f32 v[80:81], v[132:133], v[80:81]
	v_cvt_pk_bf16_f32 v72, v72, v73
	v_pk_fma_f32 v[76:77], v[140:141], v[76:77], v[80:81]
	v_or_b32_e32 v101, 48, v98
	v_pk_fma_f32 v[76:77], v[78:79], v[136:137], v[76:77]
	s_nop 0
	v_pk_add_f32 v[76:77], v[144:145], v[76:77]
	s_nop 0
	v_mul_f32_e32 v78, 0xbfb8aa3b, v76
	v_mul_f32_e32 v79, 0xbfb8aa3b, v77
	v_exp_f32_e32 v78, v78
	v_exp_f32_e32 v79, v79
	v_add_f32_e32 v78, 1.0, v78
	v_add_f32_e32 v79, 1.0, v79
	v_rcp_f32_e32 v78, v78
	v_rcp_f32_e32 v79, v79
; DI unsigned pk2(float lo, float hi) { f32x2 v = {lo, hi}; bf16x2_t b = __builtin_convertvector(v, bf16x2_t); return __builtin_bit_cast(unsigned, b); }
; DI float fexp2(float x) { return __builtin_amdgcn_exp2f(x); }
; DI float frcp(float x) { return __builtin_amdgcn_rcpf(x); }
; DI float dpp_ror1(float v) { return __int_as_float(__builtin_amdgcn_update_dpp(0, __float_as_int(v), 0x121, 0xf, 0xf, false)); }
;     __device__ __forceinline__ void operator()(const f32x4 (&acc)[2][2][4][2], const Unit& u, int wr, int wc, int fr, int fq) const {
;     ...
;                 const f32x4 w0 = *(const f32x4*)(cw + ch), w1 = *(const f32x4*)(cw + DFF + ch), w2 = *(const f32x4*)(cw + 2 * DFF + ch), bb = *(const f32x4*)(cb + ch);
;     ...
;                         const int row = u.pm * BM + ai * HALF + wr * 64 + m * 16 + fr;
;                         const f32x4 g = acc[ai][0][m][n], uu = acc[ai][1][m][n];
;                         f32x4 g1, g2, a;
; #pragma unroll
;                         for (int e = 0; e < 4; ++e) {
;                             const float c1 = dpp_ror1(g[e]), c2 = dpp_ror2(g[e]), p1 = dpp_ror1(gp[e]), p2 = dpp_ror2(gp[e]);
;                             g1[e] = (fr >= 1) ? c1 : p1; g2[e] = (fr >= 2) ? c2 : p2;
;                             const float z = w0[e] * g2[e] + w1[e] * g1[e] + w2[e] * g[e] + bb[e];
;                             a[e] = z * frcp(1.f + fexp2(-LOG2E * z)) * uu[e];
;                         }
;                         if (m > 0 || fr >= 2) { u32x2 w; w.x = pk2(a[0], a[1]); w.y = pk2(a[2], a[3]); *(u32x2*)(A2 + (size_t)row * DFF + ch) = w; }
;                         else { u32x2 w; w.x = pk2(g[0], g[1]); w.y = pk2(g[2], g[3]); *(u32x2*)(SBG + ((size_t)(row >> 6) * 4 + 2 + fr) * DFF + ch) = w;
;                                u32x2 w2_; w2_.x = pk2(uu[0], uu[1]); w2_.y = pk2(uu[2], uu[3]); *(u32x2*)(SBU + ((size_t)(row >> 6) * 2 + fr) * DFF + ch) = w2_; }
;                         if (m == 3 && fr >= 14) { u32x2 w; w.x = pk2(g[0], g[1]); w.y = pk2(g[2], g[3]); *(u32x2*)(SBG + ((size_t)(row >> 6) * 4 + (fr - 14)) * DFF + ch) = w;
;                             const int s = row & 2047; if (s >= SEQ - 2) *(f32x4*)(outp + O_FP + (size_t)l * NBP * 2 * DFF + ((size_t)(row >> 11) * 2 + (s - (SEQ - 2))) * DFF + ch) = g; }
;                         gp = g;
	s_nop 0
	v_pk_mul_f32 v[76:77], v[76:77], v[78:79]
	s_nop 0
	v_pk_mul_f32 v[74:75], v[74:75], v[76:77]
	v_cvt_pk_bf16_f32 v73, v74, v75
	v_mad_i64_i32 v[74:75], s[2:3], v100, s83, v[128:129]
	global_store_dwordx2 v[74:75], v[72:73], off
	v_mov_b32_dpp v74, v64 row_ror:2 row_mask:0xf bank_mask:0xf
	v_mov_b32_dpp v75, v65 row_ror:2 row_mask:0xf bank_mask:0xf
	v_mov_b32_dpp v72, v64 row_ror:1 row_mask:0xf bank_mask:0xf
	v_mov_b32_dpp v73, v65 row_ror:1 row_mask:0xf bank_mask:0xf
	v_cndmask_b32_e64 v75, v87, v75, s[46:47]
	v_cndmask_b32_e64 v74, v85, v74, s[46:47]
	v_cndmask_b32_e64 v73, v73, v86, s[42:43]
	v_cndmask_b32_e64 v72, v72, v84, s[42:43]
	v_pk_mul_f32 v[74:75], v[130:131], v[74:75]
	v_pk_fma_f32 v[72:73], v[138:139], v[72:73], v[74:75]
	v_pk_fma_f32 v[72:73], v[64:65], v[134:135], v[72:73]
	v_mov_b32_dpp v77, v66 row_ror:2 row_mask:0xf bank_mask:0xf
	v_pk_add_f32 v[72:73], v[142:143], v[72:73]
	v_mul_f32_e32 v74, 0xbfb8aa3b, v72
	v_mul_f32_e32 v75, 0xbfb8aa3b, v73
	v_exp_f32_e32 v74, v74
	v_exp_f32_e32 v75, v75
	v_mov_b32_dpp v79, v67 row_ror:2 row_mask:0xf bank_mask:0xf
	v_mov_b32_dpp v76, v66 row_ror:1 row_mask:0xf bank_mask:0xf
	v_add_f32_e32 v74, 1.0, v74
	v_add_f32_e32 v75, 1.0, v75
	v_rcp_f32_e32 v74, v74
	v_rcp_f32_e32 v75, v75
	v_mov_b32_dpp v78, v67 row_ror:1 row_mask:0xf bank_mask:0xf
	v_and_b32_e32 v84, 0x7ff, v101
	v_pk_mul_f32 v[72:73], v[72:73], v[74:75]
	v_cndmask_b32_e64 v75, v91, v79, s[46:47]
	v_cndmask_b32_e64 v74, v89, v77, s[46:47]
	v_pk_mul_f32 v[68:69], v[68:69], v[72:73]
	v_cndmask_b32_e64 v73, v78, v90, s[42:43]
	v_cndmask_b32_e64 v72, v76, v88, s[42:43]
	v_pk_mul_f32 v[74:75], v[132:133], v[74:75]
	v_cvt_pk_bf16_f32 v68, v68, v69
	v_pk_fma_f32 v[72:73], v[140:141], v[72:73], v[74:75]
	s_nop 0
	v_pk_fma_f32 v[72:73], v[66:67], v[136:137], v[72:73]
	s_nop 0
	v_pk_add_f32 v[72:73], v[144:145], v[72:73]
	s_nop 0
	v_mul_f32_e32 v74, 0xbfb8aa3b, v72
	v_mul_f32_e32 v75, 0xbfb8aa3b, v73
	v_exp_f32_e32 v74, v74
	v_exp_f32_e32 v75, v75
	v_add_f32_e32 v74, 1.0, v74
	v_add_f32_e32 v75, 1.0, v75
	v_rcp_f32_e32 v74, v74
	v_rcp_f32_e32 v75, v75
	s_nop 0
	v_pk_mul_f32 v[72:73], v[72:73], v[74:75]
	s_nop 0
	v_pk_mul_f32 v[70:71], v[70:71], v[72:73]
	s_nop 0
	v_cvt_pk_bf16_f32 v69, v70, v71
	v_mad_i64_i32 v[70:71], s[2:3], v101, s83, v[128:129]
	global_store_dwordx2 v[70:71], v[68:69], off
	s_and_saveexec_b64 s[2:3], s[48:49]
	s_cbranch_execz .LBB0_970
	s_ashr_i32 s36, s14, 6
	s_ashr_i32 s37, s36, 31
	v_lshl_add_u64 v[70:71], s[36:37], 2, v[160:161]
	v_mad_u64_u32 v[72:73], s[36:37], v70, s83, v[126:127]
	s_movk_i32 s6, 0x7fd
	v_cvt_pk_bf16_f32 v68, v64, v65
	v_cvt_pk_bf16_f32 v69, v66, v67
	v_mad_i32_i24 v73, v71, s83, v73
	v_cmp_lt_u32_e32 vcc, s6, v84
	global_store_dwordx2 v[72:73], v[68:69], off
	s_and_b64 exec, exec, vcc
	s_cbranch_execz .LBB0_970
	s_ashr_i32 s36, s14, 11
	s_ashr_i32 s37, s36, 31
	v_add_u32_e32 v96, 0xfffff802, v84
	v_lshl_add_u64 v[68:69], s[36:37], 1, v[96:97]
	v_mov_b64_e32 v[70:71], s[28:29]
	s_movk_i32 s6, 0x2c00
	v_mad_u64_u32 v[70:71], s[36:37], v68, s6, v[70:71]
	v_mad_i32_i24 v71, v69, s6, v71
	v_lshl_add_u64 v[68:69], v[172:173], 2, v[70:71]
	global_store_dwordx4 v[68:69], v[64:67], off
.LBB0_970:
	s_or_b64 exec, exec, s[2:3]
	v_or_b32_e32 v80, 4, v172
	v_ashrrev_i32_e32 v81, 31, v80
	v_lshlrev_b64 v[68:69], 2, v[80:81]
	v_lshl_add_u64 v[70:71], s[16:17], 0, v[68:69]
	v_lshl_add_u64 v[68:69], s[34:35], 0, v[68:69]
	global_load_dwordx4 v[64:67], v[176:177], off offset:16
	global_load_dwordx4 v[72:75], v[70:71], off
	s_nop 0
	global_load_dwordx4 v[68:71], v[68:69], off
	s_nop 0
	global_load_dwordx4 v[76:79], v[178:179], off offset:16
	v_mov_b32_dpp v90, v56 row_ror:1 row_mask:0xf bank_mask:0xf
	v_mov_b32_dpp v92, v56 row_ror:2 row_mask:0xf bank_mask:0xf
	v_mov_b32_dpp v91, v57 row_ror:1 row_mask:0xf bank_mask:0xf
	v_mov_b32_dpp v93, v57 row_ror:2 row_mask:0xf bank_mask:0xf
	v_mov_b32_dpp v86, v58 row_ror:1 row_mask:0xf bank_mask:0xf
	v_mov_b32_dpp v88, v58 row_ror:2 row_mask:0xf bank_mask:0xf
	v_mov_b32_dpp v87, v59 row_ror:1 row_mask:0xf bank_mask:0xf
	v_mov_b32_dpp v89, v59 row_ror:2 row_mask:0xf bank_mask:0xf
	s_and_saveexec_b64 s[2:3], s[44:45]
	s_xor_b64 s[2:3], exec, s[2:3]
	s_cbranch_execz .LBB0_972
	s_ashr_i32 s6, s9, 4
	v_or_b32_e32 v85, s6, v156
	v_mov_b64_e32 v[86:87], s[0:1]
	v_mad_i64_i32 v[86:87], s[34:35], v85, s83, v[86:87]
	s_ashr_i32 s16, s9, 6
	v_lshl_add_u64 v[86:87], v[80:81], 1, v[86:87]
	s_ashr_i32 s17, s16, 31
	v_add_co_u32_e32 v86, vcc, s7, v86
	v_cvt_pk_bf16_f32 v82, v56, v57
	v_cvt_pk_bf16_f32 v83, v58, v59
	v_addc_co_u32_e32 v87, vcc, 0, v87, vcc
	s_lshl_b64 s[16:17], s[16:17], 1
	global_store_dwordx2 v[86:87], v[82:83], off offset:3072
	v_cvt_pk_bf16_f32 v82, v60, v61
	v_cvt_pk_bf16_f32 v83, v62, v63
	v_mov_b32_e32 v85, s17
	v_or_b32_e32 v174, s16, v156

; DI unsigned pk2(float lo, float hi) { f32x2 v = {lo, hi}; bf16x2_t b = __builtin_convertvector(v, bf16x2_t); return __builtin_bit_cast(unsigned, b); }
; DI float fexp2(float x) { return __builtin_amdgcn_exp2f(x); }
; DI float frcp(float x) { return __builtin_amdgcn_rcpf(x); }
; DI float dpp_ror1(float v) { return __int_as_float(__builtin_amdgcn_update_dpp(0, __float_as_int(v), 0x121, 0xf, 0xf, false)); }
; DI float dpp_ror2(float v) { return __int_as_float(__builtin_amdgcn_update_dpp(0, __float_as_int(v), 0x122, 0xf, 0xf, false)); }
;     __device__ __forceinline__ void operator()(const f32x4 (&acc)[2][2][4][2], const Unit& u, int wr, int wc, int fr, int fq) const {
;     ...
;                         const int row = u.pm * BM + ai * HALF + wr * 64 + m * 16 + fr;
;                         const f32x4 g = acc[ai][0][m][n], uu = acc[ai][1][m][n];
;                         f32x4 g1, g2, a;
; #pragma unroll
;                         for (int e = 0; e < 4; ++e) {
;                             const float c1 = dpp_ror1(g[e]), c2 = dpp_ror2(g[e]), p1 = dpp_ror1(gp[e]), p2 = dpp_ror2(gp[e]);
;                             g1[e] = (fr >= 1) ? c1 : p1; g2[e] = (fr >= 2) ? c2 : p2;
;                             const float z = w0[e] * g2[e] + w1[e] * g1[e] + w2[e] * g[e] + bb[e];
;                             a[e] = z * frcp(1.f + fexp2(-LOG2E * z)) * uu[e];
;                         }
;                         if (m > 0 || fr >= 2) { u32x2 w; w.x = pk2(a[0], a[1]); w.y = pk2(a[2], a[3]); *(u32x2*)(A2 + (size_t)row * DFF + ch) = w; }
;                         else { u32x2 w; w.x = pk2(g[0], g[1]); w.y = pk2(g[2], g[3]); *(u32x2*)(SBG + ((size_t)(row >> 6) * 4 + 2 + fr) * DFF + ch) = w;
;                                u32x2 w2_; w2_.x = pk2(uu[0], uu[1]); w2_.y = pk2(uu[2], uu[3]); *(u32x2*)(SBU + ((size_t)(row >> 6) * 2 + fr) * DFF + ch) = w2_; }
;                         if (m == 3 && fr >= 14) { u32x2 w; w.x = pk2(g[0], g[1]); w.y = pk2(g[2], g[3]); *(u32x2*)(SBG + ((size_t)(row >> 6) * 4 + (fr - 14)) * DFF + ch) = w;
;                             const int s = row & 2047; if (s >= SEQ - 2) *(f32x4*)(outp + O_FP + (size_t)l * NBP * 2 * DFF + ((size_t)(row >> 11) * 2 + (s - (SEQ - 2))) * DFF + ch) = g; }
;                         gp = g;
.LBB0_974:
	s_or_b64 exec, exec, s[2:3]
	v_lshl_add_u64 v[88:89], s[66:67], 0, v[94:95]
	v_lshl_add_u64 v[88:89], v[172:173], 1, v[88:89]
	v_mad_u64_u32 v[88:89], s[2:3], v174, s83, v[88:89]
	v_mov_b32_e32 v90, v89
	v_mad_u64_u32 v[90:91], s[2:3], v85, s83, v[90:91]
	v_mov_b32_e32 v89, v90
	global_store_dwordx2 v[88:89], v[82:83], off offset:8
	v_mov_b32_dpp v83, v52 row_ror:2 row_mask:0xf bank_mask:0xf
	v_mov_b32_dpp v85, v56 row_ror:1 row_mask:0xf bank_mask:0xf
	v_mov_b32_dpp v88, v56 row_ror:2 row_mask:0xf bank_mask:0xf
	v_mov_b32_dpp v90, v53 row_ror:2 row_mask:0xf bank_mask:0xf
	v_mov_b32_dpp v91, v57 row_ror:2 row_mask:0xf bank_mask:0xf
	v_mov_b32_dpp v82, v52 row_ror:1 row_mask:0xf bank_mask:0xf
	v_mov_b32_dpp v89, v53 row_ror:1 row_mask:0xf bank_mask:0xf
	v_mov_b32_dpp v56, v57 row_ror:1 row_mask:0xf bank_mask:0xf
	v_mov_b32_dpp v94, v58 row_ror:1 row_mask:0xf bank_mask:0xf
	v_mov_b32_dpp v95, v58 row_ror:2 row_mask:0xf bank_mask:0xf
	v_mov_b32_dpp v103, v59 row_ror:1 row_mask:0xf bank_mask:0xf
	v_mov_b32_dpp v104, v59 row_ror:2 row_mask:0xf bank_mask:0xf
	v_cndmask_b32_e64 v59, v91, v90, s[46:47]
	v_cndmask_b32_e64 v58, v88, v83, s[46:47]
	v_cndmask_b32_e64 v57, v89, v56, s[42:43]
	v_cndmask_b32_e64 v56, v82, v85, s[42:43]
	s_waitcnt vmcnt(4)
	v_pk_mul_f32 v[58:59], v[64:65], v[58:59]
	s_waitcnt vmcnt(3)
	v_pk_fma_f32 v[56:57], v[72:73], v[56:57], v[58:59]
	s_waitcnt vmcnt(2)
	v_pk_fma_f32 v[52:53], v[52:53], v[68:69], v[56:57]
	s_waitcnt vmcnt(1)
	v_pk_add_f32 v[52:53], v[76:77], v[52:53]
	v_mov_b32_dpp v93, v54 row_ror:2 row_mask:0xf bank_mask:0xf
	v_mul_f32_e32 v56, 0xbfb8aa3b, v52
	v_mul_f32_e32 v57, 0xbfb8aa3b, v53
	v_exp_f32_e32 v56, v56
	v_exp_f32_e32 v57, v57
	v_mov_b32_dpp v102, v55 row_ror:2 row_mask:0xf bank_mask:0xf
	v_add_f32_e32 v56, 1.0, v56
	v_add_f32_e32 v57, 1.0, v57
	v_rcp_f32_e32 v56, v56
	v_rcp_f32_e32 v57, v57
	v_mov_b32_dpp v92, v54 row_ror:1 row_mask:0xf bank_mask:0xf
	v_mov_b32_dpp v96, v55 row_ror:1 row_mask:0xf bank_mask:0xf
	v_mad_i64_i32 v[86:87], s[2:3], v114, s83, 0
	v_pk_mul_f32 v[52:53], v[52:53], v[56:57]
	v_cndmask_b32_e64 v57, v104, v102, s[46:47]
	v_cndmask_b32_e64 v56, v95, v93, s[46:47]
	v_pk_mul_f32 v[48:49], v[48:49], v[52:53]
	v_cndmask_b32_e64 v53, v96, v103, s[42:43]
	v_cndmask_b32_e64 v52, v92, v94, s[42:43]
	v_pk_mul_f32 v[56:57], v[66:67], v[56:57]
	v_pk_fma_f32 v[52:53], v[74:75], v[52:53], v[56:57]
	v_pk_fma_f32 v[52:53], v[54:55], v[70:71], v[52:53]
	v_pk_add_f32 v[52:53], v[78:79], v[52:53]
	v_mov_b32_dpp v57, v45 row_ror:2 row_mask:0xf bank_mask:0xf
	v_mul_f32_e32 v54, 0xbfb8aa3b, v52
	v_mul_f32_e32 v55, 0xbfb8aa3b, v53
	v_exp_f32_e32 v54, v54
	v_exp_f32_e32 v55, v55
	v_mov_b32_dpp v56, v45 row_ror:1 row_mask:0xf bank_mask:0xf
	v_add_f32_e32 v54, 1.0, v54
	v_add_f32_e32 v55, 1.0, v55
	v_rcp_f32_e32 v54, v54
	v_rcp_f32_e32 v55, v55
	v_mov_b32_dpp v59, v46 row_ror:2 row_mask:0xf bank_mask:0xf
	v_mov_b32_dpp v58, v46 row_ror:1 row_mask:0xf bank_mask:0xf
	v_pk_mul_f32 v[52:53], v[52:53], v[54:55]
	v_pk_mul_f32 v[50:51], v[50:51], v[52:53]
	v_cvt_pk_bf16_f32 v52, v48, v49
	v_cvt_pk_bf16_f32 v53, v50, v51
	v_lshl_add_u64 v[50:51], s[30:31], 0, v[86:87]
	v_lshlrev_b64 v[48:49], 1, v[80:81]
	v_lshl_add_u64 v[50:51], v[50:51], 0, v[48:49]
	v_mov_b32_dpp v55, v44 row_ror:2 row_mask:0xf bank_mask:0xf
	global_store_dwordx2 v[50:51], v[52:53], off
	v_mov_b32_dpp v54, v44 row_ror:1 row_mask:0xf bank_mask:0xf
	v_cndmask_b32_e64 v53, v90, v57, s[46:47]
	v_cndmask_b32_e64 v52, v83, v55, s[46:47]
	v_cndmask_b32_e64 v51, v56, v89, s[42:43]
	v_cndmask_b32_e64 v50, v54, v82, s[42:43]
	v_pk_mul_f32 v[52:53], v[64:65], v[52:53]
	v_pk_fma_f32 v[50:51], v[72:73], v[50:51], v[52:53]
	v_mov_b32_dpp v85, v47 row_ror:1 row_mask:0xf bank_mask:0xf
	v_pk_fma_f32 v[44:45], v[44:45], v[68:69], v[50:51]
	v_mov_b32_dpp v86, v47 row_ror:2 row_mask:0xf bank_mask:0xf
	v_pk_add_f32 v[44:45], v[76:77], v[44:45]
	v_mad_i64_i32 v[62:63], s[2:3], v113, s83, 0
	v_mul_f32_e32 v50, 0xbfb8aa3b, v44
	v_mul_f32_e32 v51, 0xbfb8aa3b, v45
	v_exp_f32_e32 v50, v50
	v_exp_f32_e32 v51, v51
	v_mad_i64_i32 v[60:61], s[2:3], v115, s83, 0
	v_add_f32_e32 v50, 1.0, v50
	v_add_f32_e32 v51, 1.0, v51
	v_rcp_f32_e32 v50, v50
	v_rcp_f32_e32 v51, v51
	s_nop 0
	v_pk_mul_f32 v[44:45], v[44:45], v[50:51]
	v_cndmask_b32_e64 v51, v102, v86, s[46:47]
	v_cndmask_b32_e64 v50, v93, v59, s[46:47]
	v_pk_mul_f32 v[40:41], v[40:41], v[44:45]
	v_cndmask_b32_e64 v45, v85, v96, s[42:43]
	v_cndmask_b32_e64 v44, v58, v92, s[42:43]
	v_pk_mul_f32 v[50:51], v[66:67], v[50:51]
	v_cvt_pk_bf16_f32 v40, v40, v41
	v_pk_fma_f32 v[44:45], v[74:75], v[44:45], v[50:51]
	s_nop 0
	v_pk_fma_f32 v[44:45], v[46:47], v[70:71], v[44:45]
	s_nop 0
	v_pk_add_f32 v[44:45], v[78:79], v[44:45]
	s_nop 0
; DI unsigned pk2(float lo, float hi) { f32x2 v = {lo, hi}; bf16x2_t b = __builtin_convertvector(v, bf16x2_t); return __builtin_bit_cast(unsigned, b); }
; DI float fexp2(float x) { return __builtin_amdgcn_exp2f(x); }
; DI float frcp(float x) { return __builtin_amdgcn_rcpf(x); }
; DI float dpp_ror1(float v) { return __int_as_float(__builtin_amdgcn_update_dpp(0, __float_as_int(v), 0x121, 0xf, 0xf, false)); }
; DI float dpp_ror2(float v) { return __int_as_float(__builtin_amdgcn_update_dpp(0, __float_as_int(v), 0x122, 0xf, 0xf, false)); }
;     __device__ __forceinline__ void operator()(const f32x4 (&acc)[2][2][4][2], const Unit& u, int wr, int wc, int fr, int fq) const {
;     ...
;                         const int row = u.pm * BM + ai * HALF + wr * 64 + m * 16 + fr;
;                         const f32x4 g = acc[ai][0][m][n], uu = acc[ai][1][m][n];
;                         f32x4 g1, g2, a;
; #pragma unroll
;                         for (int e = 0; e < 4; ++e) {
;                             const float c1 = dpp_ror1(g[e]), c2 = dpp_ror2(g[e]), p1 = dpp_ror1(gp[e]), p2 = dpp_ror2(gp[e]);
;                             g1[e] = (fr >= 1) ? c1 : p1; g2[e] = (fr >= 2) ? c2 : p2;
;                             const float z = w0[e] * g2[e] + w1[e] * g1[e] + w2[e] * g[e] + bb[e];
;                             a[e] = z * frcp(1.f + fexp2(-LOG2E * z)) * uu[e];
;                         }
;                         if (m > 0 || fr >= 2) { u32x2 w; w.x = pk2(a[0], a[1]); w.y = pk2(a[2], a[3]); *(u32x2*)(A2 + (size_t)row * DFF + ch) = w; }
;                         else { u32x2 w; w.x = pk2(g[0], g[1]); w.y = pk2(g[2], g[3]); *(u32x2*)(SBG + ((size_t)(row >> 6) * 4 + 2 + fr) * DFF + ch) = w;
;                                u32x2 w2_; w2_.x = pk2(uu[0], uu[1]); w2_.y = pk2(uu[2], uu[3]); *(u32x2*)(SBU + ((size_t)(row >> 6) * 2 + fr) * DFF + ch) = w2_; }
;                         if (m == 3 && fr >= 14) { u32x2 w; w.x = pk2(g[0], g[1]); w.y = pk2(g[2], g[3]); *(u32x2*)(SBG + ((size_t)(row >> 6) * 4 + (fr - 14)) * DFF + ch) = w;
;                             const int s = row & 2047; if (s >= SEQ - 2) *(f32x4*)(outp + O_FP + (size_t)l * NBP * 2 * DFF + ((size_t)(row >> 11) * 2 + (s - (SEQ - 2))) * DFF + ch) = g; }
;                         gp = g;
	v_mul_f32_e32 v46, 0xbfb8aa3b, v44
	v_mul_f32_e32 v47, 0xbfb8aa3b, v45
	v_exp_f32_e32 v46, v46
	v_exp_f32_e32 v47, v47
	v_add_f32_e32 v46, 1.0, v46
	v_add_f32_e32 v47, 1.0, v47
	v_rcp_f32_e32 v46, v46
	v_rcp_f32_e32 v47, v47
	s_nop 0
	v_pk_mul_f32 v[44:45], v[44:45], v[46:47]
	s_nop 0
	v_pk_mul_f32 v[42:43], v[42:43], v[44:45]
	v_cvt_pk_bf16_f32 v41, v42, v43
	v_lshl_add_u64 v[42:43], s[30:31], 0, v[62:63]
	v_lshl_add_u64 v[42:43], v[42:43], 0, v[48:49]
	global_store_dwordx2 v[42:43], v[40:41], off
	v_mov_b32_dpp v42, v32 row_ror:2 row_mask:0xf bank_mask:0xf
	v_mov_b32_dpp v43, v33 row_ror:2 row_mask:0xf bank_mask:0xf
	v_mov_b32_dpp v40, v32 row_ror:1 row_mask:0xf bank_mask:0xf
	v_mov_b32_dpp v41, v33 row_ror:1 row_mask:0xf bank_mask:0xf
	v_cndmask_b32_e64 v43, v57, v43, s[46:47]
	v_cndmask_b32_e64 v42, v55, v42, s[46:47]
	v_cndmask_b32_e64 v41, v41, v56, s[42:43]
	v_cndmask_b32_e64 v40, v40, v54, s[42:43]
	v_pk_mul_f32 v[42:43], v[64:65], v[42:43]
	v_pk_fma_f32 v[40:41], v[72:73], v[40:41], v[42:43]
	v_pk_fma_f32 v[40:41], v[32:33], v[68:69], v[40:41]
	v_mov_b32_dpp v45, v34 row_ror:2 row_mask:0xf bank_mask:0xf
	v_pk_add_f32 v[40:41], v[76:77], v[40:41]
	v_mul_f32_e32 v42, 0xbfb8aa3b, v40
	v_mul_f32_e32 v43, 0xbfb8aa3b, v41
	v_exp_f32_e32 v42, v42
	v_exp_f32_e32 v43, v43
	v_mov_b32_dpp v47, v35 row_ror:2 row_mask:0xf bank_mask:0xf
	v_mov_b32_dpp v44, v34 row_ror:1 row_mask:0xf bank_mask:0xf
	v_add_f32_e32 v42, 1.0, v42
	v_add_f32_e32 v43, 1.0, v43
	v_rcp_f32_e32 v42, v42
	v_rcp_f32_e32 v43, v43
	v_mov_b32_dpp v46, v35 row_ror:1 row_mask:0xf bank_mask:0xf
	v_pk_mul_f32 v[40:41], v[40:41], v[42:43]
	v_cndmask_b32_e64 v43, v86, v47, s[46:47]
	v_cndmask_b32_e64 v42, v59, v45, s[46:47]
	v_pk_mul_f32 v[36:37], v[36:37], v[40:41]
	v_cndmask_b32_e64 v41, v46, v85, s[42:43]
	v_cndmask_b32_e64 v40, v44, v58, s[42:43]
	v_pk_mul_f32 v[42:43], v[66:67], v[42:43]
	v_cvt_pk_bf16_f32 v36, v36, v37
	v_pk_fma_f32 v[40:41], v[74:75], v[40:41], v[42:43]
	s_nop 0
	v_pk_fma_f32 v[40:41], v[34:35], v[70:71], v[40:41]
	s_nop 0
	v_pk_add_f32 v[40:41], v[78:79], v[40:41]
	s_nop 0
	v_mul_f32_e32 v42, 0xbfb8aa3b, v40
	v_mul_f32_e32 v43, 0xbfb8aa3b, v41
	v_exp_f32_e32 v42, v42
	v_exp_f32_e32 v43, v43
	v_add_f32_e32 v42, 1.0, v42
	v_add_f32_e32 v43, 1.0, v43
	v_rcp_f32_e32 v42, v42
	v_rcp_f32_e32 v43, v43
	s_nop 0
	v_pk_mul_f32 v[40:41], v[40:41], v[42:43]
	s_nop 0
	v_pk_mul_f32 v[38:39], v[38:39], v[40:41]
	s_nop 0
	v_cvt_pk_bf16_f32 v37, v38, v39
	v_lshl_add_u64 v[38:39], s[30:31], 0, v[60:61]
	v_lshl_add_u64 v[38:39], v[38:39], 0, v[48:49]
	global_store_dwordx2 v[38:39], v[36:37], off
	s_and_saveexec_b64 s[2:3], s[48:49]
	s_cbranch_execz .LBB0_977
	s_ashr_i32 s16, s9, 6
	s_ashr_i32 s17, s16, 31
	v_lshl_add_u64 v[38:39], s[16:17], 2, v[160:161]
	v_mov_b64_e32 v[40:41], s[0:1]
	v_mad_u64_u32 v[40:41], s[16:17], v38, s83, v[40:41]
	v_mad_i32_i24 v41, v39, s83, v41
	s_movk_i32 s6, 0x7fd
	v_cvt_pk_bf16_f32 v36, v32, v33
	v_cvt_pk_bf16_f32 v37, v34, v35
	v_lshl_add_u64 v[38:39], v[80:81], 1, v[40:41]
	v_cmp_lt_u32_e32 vcc, s6, v112
	global_store_dwordx2 v[38:39], v[36:37], off
	s_and_b64 exec, exec, vcc
	s_cbranch_execz .LBB0_977
	s_ashr_i32 s16, s9, 11
	s_ashr_i32 s17, s16, 31
	v_add_u32_e32 v96, 0xfffff802, v112
	v_lshl_add_u64 v[36:37], s[16:17], 1, v[96:97]
	v_mov_b64_e32 v[38:39], s[28:29]
	s_movk_i32 s6, 0x2c00
	v_mad_u64_u32 v[38:39], s[16:17], v36, s6, v[38:39]
	v_mad_i32_i24 v39, v37, s6, v39
	v_lshl_add_u64 v[36:37], v[172:173], 2, v[38:39]
	global_store_dwordx4 v[36:37], v[32:35], off offset:16
.LBB0_977:
	s_or_b64 exec, exec, s[2:3]
	s_nop 1
	v_mov_b32_dpp v38, v24 row_ror:1 row_mask:0xf bank_mask:0xf
	v_mov_b32_dpp v40, v24 row_ror:2 row_mask:0xf bank_mask:0xf
	v_mov_b32_dpp v39, v25 row_ror:1 row_mask:0xf bank_mask:0xf
	v_mov_b32_dpp v41, v25 row_ror:2 row_mask:0xf bank_mask:0xf
	v_mov_b32_dpp v34, v26 row_ror:1 row_mask:0xf bank_mask:0xf
	v_mov_b32_dpp v36, v26 row_ror:2 row_mask:0xf bank_mask:0xf
	v_mov_b32_dpp v35, v27 row_ror:1 row_mask:0xf bank_mask:0xf
	v_mov_b32_dpp v37, v27 row_ror:2 row_mask:0xf bank_mask:0xf
	s_and_saveexec_b64 s[2:3], s[44:45]
	s_xor_b64 s[2:3], exec, s[2:3]
	s_cbranch_execz .LBB0_979
	s_ashr_i32 s6, s14, 4
	v_or_b32_e32 v36, s6, v156
	v_mov_b64_e32 v[34:35], s[0:1]
	v_mad_i64_i32 v[34:35], s[34:35], v36, s83, v[34:35]
	s_ashr_i32 s16, s14, 6
	v_lshl_add_u64 v[34:35], v[80:81], 1, v[34:35]
	s_ashr_i32 s17, s16, 31
	v_add_co_u32_e32 v34, vcc, s7, v34
	v_cvt_pk_bf16_f32 v32, v24, v25
	v_cvt_pk_bf16_f32 v33, v26, v27
	v_addc_co_u32_e32 v35, vcc, 0, v35, vcc
	s_lshl_b64 s[16:17], s[16:17], 1
	global_store_dwordx2 v[34:35], v[32:33], off offset:3072
	v_cvt_pk_bf16_f32 v32, v28, v29
	v_cvt_pk_bf16_f32 v33, v30, v31
	v_mov_b32_e32 v43, s17
	v_or_b32_e32 v98, s16, v156

; DI unsigned pk2(float lo, float hi) { f32x2 v = {lo, hi}; bf16x2_t b = __builtin_convertvector(v, bf16x2_t); return __builtin_bit_cast(unsigned, b); }
; DI float fexp2(float x) { return __builtin_amdgcn_exp2f(x); }
; DI float frcp(float x) { return __builtin_amdgcn_rcpf(x); }
; DI float dpp_ror1(float v) { return __int_as_float(__builtin_amdgcn_update_dpp(0, __float_as_int(v), 0x121, 0xf, 0xf, false)); }
; DI float dpp_ror2(float v) { return __int_as_float(__builtin_amdgcn_update_dpp(0, __float_as_int(v), 0x122, 0xf, 0xf, false)); }
;     __device__ __forceinline__ void operator()(const f32x4 (&acc)[2][2][4][2], const Unit& u, int wr, int wc, int fr, int fq) const {
;     ...
;                         const int row = u.pm * BM + ai * HALF + wr * 64 + m * 16 + fr;
;                         const f32x4 g = acc[ai][0][m][n], uu = acc[ai][1][m][n];
;                         f32x4 g1, g2, a;
; #pragma unroll
;                         for (int e = 0; e < 4; ++e) {
;                             const float c1 = dpp_ror1(g[e]), c2 = dpp_ror2(g[e]), p1 = dpp_ror1(gp[e]), p2 = dpp_ror2(gp[e]);
;                             g1[e] = (fr >= 1) ? c1 : p1; g2[e] = (fr >= 2) ? c2 : p2;
;                             const float z = w0[e] * g2[e] + w1[e] * g1[e] + w2[e] * g[e] + bb[e];
;                             a[e] = z * frcp(1.f + fexp2(-LOG2E * z)) * uu[e];
;                         }
;                         if (m > 0 || fr >= 2) { u32x2 w; w.x = pk2(a[0], a[1]); w.y = pk2(a[2], a[3]); *(u32x2*)(A2 + (size_t)row * DFF + ch) = w; }
;                         else { u32x2 w; w.x = pk2(g[0], g[1]); w.y = pk2(g[2], g[3]); *(u32x2*)(SBG + ((size_t)(row >> 6) * 4 + 2 + fr) * DFF + ch) = w;
;                                u32x2 w2_; w2_.x = pk2(uu[0], uu[1]); w2_.y = pk2(uu[2], uu[3]); *(u32x2*)(SBU + ((size_t)(row >> 6) * 2 + fr) * DFF + ch) = w2_; }
;                         if (m == 3 && fr >= 14) { u32x2 w; w.x = pk2(g[0], g[1]); w.y = pk2(g[2], g[3]); *(u32x2*)(SBG + ((size_t)(row >> 6) * 4 + (fr - 14)) * DFF + ch) = w;
;                             const int s = row & 2047; if (s >= SEQ - 2) *(f32x4*)(outp + O_FP + (size_t)l * NBP * 2 * DFF + ((size_t)(row >> 11) * 2 + (s - (SEQ - 2))) * DFF + ch) = g; }
;                         gp = g;
.LBB0_981:
	s_or_b64 exec, exec, s[2:3]
	v_lshl_add_u64 v[36:37], s[66:67], 0, v[44:45]
	v_lshl_add_u64 v[36:37], v[172:173], 1, v[36:37]
	v_mad_u64_u32 v[36:37], s[2:3], v98, s83, v[36:37]
	v_mov_b32_e32 v38, v37
	v_mad_u64_u32 v[38:39], s[2:3], v43, s83, v[38:39]
	v_mov_b32_e32 v37, v38
	global_store_dwordx2 v[36:37], v[32:33], off offset:8
	v_mov_b32_dpp v33, v20 row_ror:2 row_mask:0xf bank_mask:0xf
	v_mov_b32_dpp v36, v24 row_ror:1 row_mask:0xf bank_mask:0xf
	v_mov_b32_dpp v37, v24 row_ror:2 row_mask:0xf bank_mask:0xf
	v_mov_b32_dpp v39, v21 row_ror:2 row_mask:0xf bank_mask:0xf
	v_mov_b32_dpp v40, v25 row_ror:2 row_mask:0xf bank_mask:0xf
	v_mov_b32_dpp v32, v20 row_ror:1 row_mask:0xf bank_mask:0xf
	v_mov_b32_dpp v38, v21 row_ror:1 row_mask:0xf bank_mask:0xf
	v_mov_b32_dpp v24, v25 row_ror:1 row_mask:0xf bank_mask:0xf
	v_mov_b32_dpp v43, v26 row_ror:1 row_mask:0xf bank_mask:0xf
	v_mov_b32_dpp v44, v26 row_ror:2 row_mask:0xf bank_mask:0xf
	v_mov_b32_dpp v47, v27 row_ror:1 row_mask:0xf bank_mask:0xf
	v_mov_b32_dpp v50, v27 row_ror:2 row_mask:0xf bank_mask:0xf
	v_cndmask_b32_e64 v27, v40, v39, s[46:47]
	v_cndmask_b32_e64 v26, v37, v33, s[46:47]
	v_cndmask_b32_e64 v25, v38, v24, s[42:43]
	v_cndmask_b32_e64 v24, v32, v36, s[42:43]
	v_pk_mul_f32 v[26:27], v[64:65], v[26:27]
	v_pk_fma_f32 v[24:25], v[72:73], v[24:25], v[26:27]
	v_pk_fma_f32 v[20:21], v[20:21], v[68:69], v[24:25]
	v_pk_add_f32 v[20:21], v[76:77], v[20:21]
	v_mov_b32_dpp v42, v22 row_ror:2 row_mask:0xf bank_mask:0xf
	v_mul_f32_e32 v24, 0xbfb8aa3b, v20
	v_mul_f32_e32 v25, 0xbfb8aa3b, v21
	v_exp_f32_e32 v24, v24
	v_exp_f32_e32 v25, v25
	v_mov_b32_dpp v46, v23 row_ror:2 row_mask:0xf bank_mask:0xf
	v_add_f32_e32 v24, 1.0, v24
	v_add_f32_e32 v25, 1.0, v25
	v_rcp_f32_e32 v24, v24
	v_rcp_f32_e32 v25, v25
	v_mov_b32_dpp v41, v22 row_ror:1 row_mask:0xf bank_mask:0xf
	v_mov_b32_dpp v45, v23 row_ror:1 row_mask:0xf bank_mask:0xf
	v_mad_i64_i32 v[34:35], s[2:3], v99, s83, 0
	v_pk_mul_f32 v[20:21], v[20:21], v[24:25]
	v_cndmask_b32_e64 v25, v50, v46, s[46:47]
	v_cndmask_b32_e64 v24, v44, v42, s[46:47]
	v_pk_mul_f32 v[16:17], v[16:17], v[20:21]
	v_cndmask_b32_e64 v21, v45, v47, s[42:43]
	v_cndmask_b32_e64 v20, v41, v43, s[42:43]
	v_pk_mul_f32 v[24:25], v[66:67], v[24:25]
	v_cvt_pk_bf16_f32 v16, v16, v17
	v_pk_fma_f32 v[20:21], v[74:75], v[20:21], v[24:25]
	v_pk_fma_f32 v[20:21], v[22:23], v[70:71], v[20:21]
	v_pk_add_f32 v[20:21], v[78:79], v[20:21]
	v_mul_f32_e32 v22, 0xbfb8aa3b, v20
	v_mul_f32_e32 v23, 0xbfb8aa3b, v21
	v_exp_f32_e32 v22, v22
	v_exp_f32_e32 v23, v23
	v_mov_b32_dpp v25, v14 row_ror:2 row_mask:0xf bank_mask:0xf
	v_add_f32_e32 v22, 1.0, v22
	v_add_f32_e32 v23, 1.0, v23
	v_rcp_f32_e32 v22, v22
	v_rcp_f32_e32 v23, v23
	v_mov_b32_dpp v27, v15 row_ror:2 row_mask:0xf bank_mask:0xf
	v_mov_b32_dpp v24, v14 row_ror:1 row_mask:0xf bank_mask:0xf
	v_mov_b32_dpp v26, v15 row_ror:1 row_mask:0xf bank_mask:0xf
	v_pk_mul_f32 v[20:21], v[20:21], v[22:23]
	v_pk_mul_f32 v[18:19], v[18:19], v[20:21]
	v_cvt_pk_bf16_f32 v17, v18, v19
	v_lshl_add_u64 v[18:19], s[30:31], 0, v[34:35]
	v_lshl_add_u64 v[18:19], v[18:19], 0, v[48:49]
	v_mov_b32_dpp v21, v12 row_ror:2 row_mask:0xf bank_mask:0xf
	v_mov_b32_dpp v23, v13 row_ror:2 row_mask:0xf bank_mask:0xf
	global_store_dwordx2 v[18:19], v[16:17], off
	v_mov_b32_dpp v20, v12 row_ror:1 row_mask:0xf bank_mask:0xf
	v_mov_b32_dpp v22, v13 row_ror:1 row_mask:0xf bank_mask:0xf
	v_cndmask_b32_e64 v19, v39, v23, s[46:47]
	v_cndmask_b32_e64 v18, v33, v21, s[46:47]
	v_cndmask_b32_e64 v17, v22, v38, s[42:43]
	v_cndmask_b32_e64 v16, v20, v32, s[42:43]
	v_pk_mul_f32 v[18:19], v[64:65], v[18:19]
	v_mad_i64_i32 v[30:31], s[2:3], v100, s83, 0
	v_pk_fma_f32 v[16:17], v[72:73], v[16:17], v[18:19]
	v_mad_i64_i32 v[28:29], s[2:3], v101, s83, 0
	v_pk_fma_f32 v[12:13], v[12:13], v[68:69], v[16:17]
	s_nop 0
	v_pk_add_f32 v[12:13], v[76:77], v[12:13]
	s_nop 0
	v_mul_f32_e32 v16, 0xbfb8aa3b, v12
	v_mul_f32_e32 v17, 0xbfb8aa3b, v13
	v_exp_f32_e32 v16, v16
	v_exp_f32_e32 v17, v17
; DI unsigned pk2(float lo, float hi) { f32x2 v = {lo, hi}; bf16x2_t b = __builtin_convertvector(v, bf16x2_t); return __builtin_bit_cast(unsigned, b); }
; DI float fexp2(float x) { return __builtin_amdgcn_exp2f(x); }
; DI float frcp(float x) { return __builtin_amdgcn_rcpf(x); }
; DI float dpp_ror1(float v) { return __int_as_float(__builtin_amdgcn_update_dpp(0, __float_as_int(v), 0x121, 0xf, 0xf, false)); }
; DI float dpp_ror2(float v) { return __int_as_float(__builtin_amdgcn_update_dpp(0, __float_as_int(v), 0x122, 0xf, 0xf, false)); }
;     __device__ __forceinline__ void operator()(const f32x4 (&acc)[2][2][4][2], const Unit& u, int wr, int wc, int fr, int fq) const {
;     ...
;                         const int row = u.pm * BM + ai * HALF + wr * 64 + m * 16 + fr;
;                         const f32x4 g = acc[ai][0][m][n], uu = acc[ai][1][m][n];
;                         f32x4 g1, g2, a;
; #pragma unroll
;                         for (int e = 0; e < 4; ++e) {
;                             const float c1 = dpp_ror1(g[e]), c2 = dpp_ror2(g[e]), p1 = dpp_ror1(gp[e]), p2 = dpp_ror2(gp[e]);
;                             g1[e] = (fr >= 1) ? c1 : p1; g2[e] = (fr >= 2) ? c2 : p2;
;                             const float z = w0[e] * g2[e] + w1[e] * g1[e] + w2[e] * g[e] + bb[e];
;                             a[e] = z * frcp(1.f + fexp2(-LOG2E * z)) * uu[e];
;                         }
;                         if (m > 0 || fr >= 2) { u32x2 w; w.x = pk2(a[0], a[1]); w.y = pk2(a[2], a[3]); *(u32x2*)(A2 + (size_t)row * DFF + ch) = w; }
;                         else { u32x2 w; w.x = pk2(g[0], g[1]); w.y = pk2(g[2], g[3]); *(u32x2*)(SBG + ((size_t)(row >> 6) * 4 + 2 + fr) * DFF + ch) = w;
;                                u32x2 w2_; w2_.x = pk2(uu[0], uu[1]); w2_.y = pk2(uu[2], uu[3]); *(u32x2*)(SBU + ((size_t)(row >> 6) * 2 + fr) * DFF + ch) = w2_; }
;                         if (m == 3 && fr >= 14) { u32x2 w; w.x = pk2(g[0], g[1]); w.y = pk2(g[2], g[3]); *(u32x2*)(SBG + ((size_t)(row >> 6) * 4 + (fr - 14)) * DFF + ch) = w;
;                             const int s = row & 2047; if (s >= SEQ - 2) *(f32x4*)(outp + O_FP + (size_t)l * NBP * 2 * DFF + ((size_t)(row >> 11) * 2 + (s - (SEQ - 2))) * DFF + ch) = g; }
;                         gp = g;
	v_add_f32_e32 v16, 1.0, v16
	v_add_f32_e32 v17, 1.0, v17
	v_rcp_f32_e32 v16, v16
	v_rcp_f32_e32 v17, v17
	s_nop 0
	v_pk_mul_f32 v[12:13], v[12:13], v[16:17]
	v_cndmask_b32_e64 v17, v46, v27, s[46:47]
	v_cndmask_b32_e64 v16, v42, v25, s[46:47]
	v_pk_mul_f32 v[8:9], v[8:9], v[12:13]
	v_cndmask_b32_e64 v13, v26, v45, s[42:43]
	v_cndmask_b32_e64 v12, v24, v41, s[42:43]
	v_pk_mul_f32 v[16:17], v[66:67], v[16:17]
	v_cvt_pk_bf16_f32 v8, v8, v9
	v_pk_fma_f32 v[12:13], v[74:75], v[12:13], v[16:17]
	s_nop 0
	v_pk_fma_f32 v[12:13], v[14:15], v[70:71], v[12:13]
	s_nop 0
	v_pk_add_f32 v[12:13], v[78:79], v[12:13]
	s_nop 0
	v_mul_f32_e32 v14, 0xbfb8aa3b, v12
	v_mul_f32_e32 v15, 0xbfb8aa3b, v13
	v_exp_f32_e32 v14, v14
	v_exp_f32_e32 v15, v15
	v_add_f32_e32 v14, 1.0, v14
	v_add_f32_e32 v15, 1.0, v15
	v_rcp_f32_e32 v14, v14
	v_rcp_f32_e32 v15, v15
	s_nop 0
	v_pk_mul_f32 v[12:13], v[12:13], v[14:15]
	s_nop 0
	v_pk_mul_f32 v[10:11], v[10:11], v[12:13]
	v_cvt_pk_bf16_f32 v9, v10, v11
	v_lshl_add_u64 v[10:11], s[30:31], 0, v[30:31]
	v_lshl_add_u64 v[10:11], v[10:11], 0, v[48:49]
	global_store_dwordx2 v[10:11], v[8:9], off
	v_mov_b32_dpp v10, v0 row_ror:2 row_mask:0xf bank_mask:0xf
	v_mov_b32_dpp v11, v1 row_ror:2 row_mask:0xf bank_mask:0xf
	v_mov_b32_dpp v8, v0 row_ror:1 row_mask:0xf bank_mask:0xf
	v_mov_b32_dpp v9, v1 row_ror:1 row_mask:0xf bank_mask:0xf
	v_cndmask_b32_e64 v11, v23, v11, s[46:47]
	v_cndmask_b32_e64 v10, v21, v10, s[46:47]
	v_cndmask_b32_e64 v9, v9, v22, s[42:43]
	v_cndmask_b32_e64 v8, v8, v20, s[42:43]
	v_pk_mul_f32 v[10:11], v[64:65], v[10:11]
	v_pk_fma_f32 v[8:9], v[72:73], v[8:9], v[10:11]
	v_pk_fma_f32 v[8:9], v[0:1], v[68:69], v[8:9]
	v_mov_b32_dpp v13, v2 row_ror:2 row_mask:0xf bank_mask:0xf
	v_pk_add_f32 v[8:9], v[76:77], v[8:9]
	v_mul_f32_e32 v10, 0xbfb8aa3b, v8
	v_mul_f32_e32 v11, 0xbfb8aa3b, v9
	v_exp_f32_e32 v10, v10
	v_exp_f32_e32 v11, v11
	v_mov_b32_dpp v15, v3 row_ror:2 row_mask:0xf bank_mask:0xf
	v_mov_b32_dpp v12, v2 row_ror:1 row_mask:0xf bank_mask:0xf
	v_add_f32_e32 v10, 1.0, v10
	v_add_f32_e32 v11, 1.0, v11
	v_rcp_f32_e32 v10, v10
	v_rcp_f32_e32 v11, v11
	v_mov_b32_dpp v14, v3 row_ror:1 row_mask:0xf bank_mask:0xf
	v_pk_mul_f32 v[8:9], v[8:9], v[10:11]
	v_cndmask_b32_e64 v11, v27, v15, s[46:47]
	v_cndmask_b32_e64 v10, v25, v13, s[46:47]
	v_pk_mul_f32 v[4:5], v[4:5], v[8:9]
	v_cndmask_b32_e64 v9, v14, v26, s[42:43]
	v_cndmask_b32_e64 v8, v12, v24, s[42:43]
	v_pk_mul_f32 v[10:11], v[66:67], v[10:11]
	v_cvt_pk_bf16_f32 v4, v4, v5
	v_pk_fma_f32 v[8:9], v[74:75], v[8:9], v[10:11]
	s_nop 0
	v_pk_fma_f32 v[8:9], v[2:3], v[70:71], v[8:9]
	s_nop 0
	v_pk_add_f32 v[8:9], v[78:79], v[8:9]
	s_nop 0
	v_mul_f32_e32 v10, 0xbfb8aa3b, v8
	v_mul_f32_e32 v11, 0xbfb8aa3b, v9
	v_exp_f32_e32 v10, v10
	v_exp_f32_e32 v11, v11
	v_add_f32_e32 v10, 1.0, v10
	v_add_f32_e32 v11, 1.0, v11
	v_rcp_f32_e32 v10, v10
	v_rcp_f32_e32 v11, v11
	s_nop 0
	v_pk_mul_f32 v[8:9], v[8:9], v[10:11]
	s_nop 0
	v_pk_mul_f32 v[6:7], v[6:7], v[8:9]
	s_nop 0
	v_cvt_pk_bf16_f32 v5, v6, v7
	v_lshl_add_u64 v[6:7], s[30:31], 0, v[28:29]
	v_lshl_add_u64 v[6:7], v[6:7], 0, v[48:49]
	global_store_dwordx2 v[6:7], v[4:5], off
	s_and_saveexec_b64 s[2:3], s[48:49]
	s_cbranch_execz .LBB0_984
	s_ashr_i32 s16, s14, 6
	s_ashr_i32 s17, s16, 31
	v_lshl_add_u64 v[6:7], s[16:17], 2, v[160:161]
	v_mov_b64_e32 v[8:9], s[0:1]
	v_mad_u64_u32 v[8:9], s[0:1], v6, s83, v[8:9]
	v_mad_i32_i24 v9, v7, s83, v9
	s_movk_i32 s0, 0x7fd
	v_cvt_pk_bf16_f32 v4, v0, v1
	v_cvt_pk_bf16_f32 v5, v2, v3
	v_lshl_add_u64 v[6:7], v[80:81], 1, v[8:9]
	v_cmp_lt_u32_e32 vcc, s0, v84
	global_store_dwordx2 v[6:7], v[4:5], off
	s_and_b64 exec, exec, vcc
	s_cbranch_execz .LBB0_984
	s_ashr_i32 s0, s14, 11
	s_ashr_i32 s1, s0, 31
	v_add_u32_e32 v96, 0xfffff802, v84
	v_lshl_add_u64 v[4:5], s[0:1], 1, v[96:97]
	v_mov_b64_e32 v[6:7], s[28:29]
	s_movk_i32 s6, 0x2c00
	v_mad_u64_u32 v[6:7], s[0:1], v4, s6, v[6:7]
	v_mad_i32_i24 v7, v5, s6, v7
	v_lshl_add_u64 v[4:5], v[172:173], 2, v[6:7]
	global_store_dwordx4 v[4:5], v[0:3], off offset:16

; #define LAS __attribute__((address_space(3)))
; DI void phase_prep(ArgsP AP, LAS unsigned char* lds) {
;     ...
;             const float* wp = adaw + ((size_t)l * 1024 + wave * 128) * 6144 + cgp * 128 + 2 * lane;
;             for (int k4 = 0; k4 < 32; ++k4) {
;                 f32x2 wv[4];
; #pragma unroll
;                 for (int kk = 0; kk < 4; ++kk) wv[kk] = *(const f32x2*)(wp + (size_t)(k4 * 4 + kk) * 6144);
; #pragma unroll
;                 for (int b = 0; b < 24; ++b) {
;                     const f32x4 cv = *(const LAS f32x4*)(cs + b * 1024 + wave * 128 + k4 * 4);
;                     acc[b][0] += cv[0] * wv[0][0] + cv[1] * wv[1][0] + cv[2] * wv[2][0] + cv[3] * wv[3][0];
;                     acc[b][1] += cv[0] * wv[0][1] + cv[1] * wv[1][1] + cv[2] * wv[2][1] + cv[3] * wv[3][1];
;                 }
;             }
.LBB0_1165:
	s_or_b64 exec, exec, s[0:1]
	s_mul_hi_i32 s0, s17, 0x2aaaaaab
	s_lshr_b32 s1, s0, 31
	s_ashr_i32 s0, s0, 3
	s_add_i32 s14, s0, s1
	s_mul_i32 s0, s14, 48
	s_sub_i32 s0, s17, s0
	s_lshl_b32 s0, s0, 7
	s_ashr_i32 s1, s0, 31
	s_mul_i32 s7, s14, 0x1800000
	s_lshl_b64 s[2:3], s[0:1], 2
	s_mul_hi_i32 s6, s14, 0x1800000
	s_add_u32 s2, s7, s2
	s_addc_u32 s3, s6, s3
	v_mov_b32_e32 v10, 0
	v_lshl_add_u64 v[12:13], v[8:9], 0, s[2:3]
	s_mov_b32 s2, 0
	v_mov_b32_e32 v11, v10
	v_mov_b32_e32 v14, v10
	v_mov_b32_e32 v15, v10
	v_mov_b32_e32 v16, v10
	v_mov_b32_e32 v17, v10
	v_mov_b32_e32 v18, v10
	v_mov_b32_e32 v19, v10
	v_mov_b32_e32 v20, v10
	v_mov_b32_e32 v21, v10
	v_mov_b32_e32 v22, v10
	v_mov_b32_e32 v23, v10
	v_mov_b32_e32 v24, v10
	v_mov_b32_e32 v25, v10
	v_mov_b32_e32 v26, v10
	v_mov_b32_e32 v27, v10
	v_mov_b32_e32 v28, v10
	v_mov_b32_e32 v29, v10
	v_mov_b32_e32 v30, v10
	v_mov_b32_e32 v31, v10
	v_mov_b32_e32 v32, v10
	v_mov_b32_e32 v33, v10
	v_mov_b32_e32 v34, v10
	v_mov_b32_e32 v35, v10
	v_mov_b32_e32 v36, v10
	v_mov_b32_e32 v37, v10
	v_mov_b32_e32 v38, v10
	v_mov_b32_e32 v39, v10
	v_mov_b32_e32 v40, v10
	v_mov_b32_e32 v41, v10
	v_mov_b32_e32 v42, v10
	v_mov_b32_e32 v43, v10
	v_mov_b32_e32 v44, v10
	v_mov_b32_e32 v45, v10
	v_mov_b32_e32 v46, v10
	v_mov_b32_e32 v47, v10
	v_mov_b32_e32 v48, v10
	v_mov_b32_e32 v49, v10
	v_mov_b32_e32 v50, v10
	v_mov_b32_e32 v51, v10
	v_mov_b32_e32 v52, v10
	v_mov_b32_e32 v53, v10
	v_mov_b32_e32 v54, v10
	v_mov_b32_e32 v55, v10
	v_mov_b32_e32 v56, v10
	v_mov_b32_e32 v57, v10
	v_mov_b32_e32 v58, v10
	v_mov_b32_e32 v59, v10
	s_waitcnt vmcnt(0) lgkmcnt(0)
	s_mov_b32 s3, 0xfffee000
	v_add_co_u32_e32 v60, vcc, s3, v12
	s_mov_b32 s3, 0xffff4000
	s_nop 0
	v_addc_co_u32_e32 v61, vcc, -1, v13, vcc
	v_add_co_u32_e32 v66, vcc, s3, v12
	global_load_dwordx2 v[60:61], v[60:61], off
	s_nop 0
	v_addc_co_u32_e32 v67, vcc, -1, v13, vcc
	global_load_dwordx2 v[70:71], v[66:67], off
	s_movk_i32 s3, 0xa000
	v_add_co_u32_e32 v66, vcc, s3, v12
	s_nop 1
	v_addc_co_u32_e32 v67, vcc, -1, v13, vcc
	global_load_dwordx2 v[72:73], v[66:67], off
	global_load_dwordx2 v[74:75], v[12:13], off
	s_mov_b64 s[18:19], 0x18000
	v_lshl_add_u64 v[12:13], v[12:13], 0, s[18:19]
	s_mov_b32 s3, 0xfffee000
	v_add_co_u32_e32 v108, vcc, s3, v12
	s_mov_b32 s3, 0xffff4000
	s_nop 0
	v_addc_co_u32_e32 v109, vcc, -1, v13, vcc
	v_add_co_u32_e32 v66, vcc, s3, v12
	global_load_dwordx2 v[108:109], v[108:109], off
	s_nop 0
	v_addc_co_u32_e32 v67, vcc, -1, v13, vcc
	global_load_dwordx2 v[110:111], v[66:67], off
	s_movk_i32 s3, 0xa000
	v_add_co_u32_e32 v66, vcc, s3, v12
	s_nop 1
	v_addc_co_u32_e32 v67, vcc, -1, v13, vcc
	global_load_dwordx2 v[112:113], v[66:67], off
	global_load_dwordx2 v[114:115], v[12:13], off
	s_barrier
.LBB0_1166:
	s_waitcnt vmcnt(4)
	v_mov_b64_e32 v[78:79], v[60:61]
	v_mov_b64_e32 v[80:81], v[70:71]
	v_mov_b64_e32 v[82:83], v[72:73]
	v_mov_b64_e32 v[84:85], v[74:75]
	s_add_i32 s3, s16, s2
	s_add_i32 s6, s3, 0x10000
	v_mov_b32_e32 v65, s3
	v_mov_b32_e32 v98, s6
	s_add_i32 s2, s2, 16
	s_cmpk_lt_u32 s2, 0x1f0
	s_cselect_b32 s18, 0x18000, 0
	s_mov_b32 s19, 0
	v_lshl_add_u64 v[12:13], v[12:13], 0, s[18:19]
	ds_read_b128 v[86:89], v65
	ds_read_b128 v[90:93], v65 offset:4096
	ds_read_b128 v[100:103], v65 offset:8192
	s_mov_b32 s3, 0xfffee000
	v_add_co_u32_e32 v60, vcc, s3, v12
	s_mov_b32 s3, 0xffff4000
	s_nop 0
	v_addc_co_u32_e32 v61, vcc, -1, v13, vcc
	v_add_co_u32_e32 v66, vcc, s3, v12
	global_load_dwordx2 v[60:61], v[60:61], off
	s_nop 0
	v_addc_co_u32_e32 v67, vcc, -1, v13, vcc
	global_load_dwordx2 v[70:71], v[66:67], off
	s_movk_i32 s3, 0xa000
	v_add_co_u32_e32 v66, vcc, s3, v12
	s_nop 1
	v_addc_co_u32_e32 v67, vcc, -1, v13, vcc
	global_load_dwordx2 v[72:73], v[66:67], off
	global_load_dwordx2 v[74:75], v[12:13], off
	ds_read_b128 v[104:107], v65 offset:12288
	s_waitcnt lgkmcnt(3)
	v_pk_mul_f32 v[76:77], v[80:81], v[86:87] op_sel:[0,1]
	s_nop 0
	v_pk_fma_f32 v[66:67], v[78:79], v[86:87], v[76:77] op_sel_hi:[1,0,1]
	s_nop 0
	v_pk_fma_f32 v[66:67], v[82:83], v[88:89], v[66:67] op_sel_hi:[1,0,1]
	v_mov_b32_e32 v88, v89
	v_pk_fma_f32 v[66:67], v[84:85], v[88:89], v[66:67] op_sel_hi:[1,0,1]
	s_nop 0
	v_pk_add_f32 v[10:11], v[10:11], v[66:67]
	ds_read_b128 v[86:89], v65 offset:16384
	s_waitcnt lgkmcnt(3)
	v_pk_mul_f32 v[76:77], v[80:81], v[90:91] op_sel:[0,1]
	s_nop 0
	v_pk_fma_f32 v[66:67], v[78:79], v[90:91], v[76:77] op_sel_hi:[1,0,1]
	s_nop 0
	v_pk_fma_f32 v[66:67], v[82:83], v[92:93], v[66:67] op_sel_hi:[1,0,1]
	v_mov_b32_e32 v92, v93
	v_pk_fma_f32 v[66:67], v[84:85], v[92:93], v[66:67] op_sel_hi:[1,0,1]
	s_nop 0
	v_pk_add_f32 v[14:15], v[14:15], v[66:67]
	ds_read_b128 v[90:93], v65 offset:20480
	s_waitcnt lgkmcnt(3)
	v_pk_mul_f32 v[76:77], v[80:81], v[100:101] op_sel:[0,1]
	s_nop 0
	v_pk_fma_f32 v[66:67], v[78:79], v[100:101], v[76:77] op_sel_hi:[1,0,1]
	s_nop 0
	v_pk_fma_f32 v[66:67], v[82:83], v[102:103], v[66:67] op_sel_hi:[1,0,1]
	v_mov_b32_e32 v102, v103
	v_pk_fma_f32 v[66:67], v[84:85], v[102:103], v[66:67] op_sel_hi:[1,0,1]
	s_nop 0
	v_pk_add_f32 v[16:17], v[16:17], v[66:67]
	ds_read_b128 v[100:103], v65 offset:24576
	s_waitcnt lgkmcnt(3)
	v_pk_mul_f32 v[76:77], v[80:81], v[104:105] op_sel:[0,1]
	s_nop 0
	v_pk_fma_f32 v[66:67], v[78:79], v[104:105], v[76:77] op_sel_hi:[1,0,1]
	s_nop 0
	v_pk_fma_f32 v[66:67], v[82:83], v[106:107], v[66:67] op_sel_hi:[1,0,1]
	v_mov_b32_e32 v106, v107
	v_pk_fma_f32 v[66:67], v[84:85], v[106:107], v[66:67] op_sel_hi:[1,0,1]
	s_nop 0
	v_pk_add_f32 v[18:19], v[18:19], v[66:67]
	ds_read_b128 v[104:107], v65 offset:28672
	s_waitcnt lgkmcnt(3)
; #define LAS __attribute__((address_space(3)))
; DI void phase_prep(ArgsP AP, LAS unsigned char* lds) {
;     ...
; #pragma unroll
;                 for (int b = 0; b < 24; ++b) {
;                     const f32x4 cv = *(const LAS f32x4*)(cs + b * 1024 + wave * 128 + k4 * 4);
;                     acc[b][0] += cv[0] * wv[0][0] + cv[1] * wv[1][0] + cv[2] * wv[2][0] + cv[3] * wv[3][0];
;                     acc[b][1] += cv[0] * wv[0][1] + cv[1] * wv[1][1] + cv[2] * wv[2][1] + cv[3] * wv[3][1];
;                 }
	v_pk_mul_f32 v[76:77], v[80:81], v[86:87] op_sel:[0,1]
	s_nop 0
	v_pk_fma_f32 v[66:67], v[78:79], v[86:87], v[76:77] op_sel_hi:[1,0,1]
	s_nop 0
	v_pk_fma_f32 v[66:67], v[82:83], v[88:89], v[66:67] op_sel_hi:[1,0,1]
	v_mov_b32_e32 v88, v89
	v_pk_fma_f32 v[66:67], v[84:85], v[88:89], v[66:67] op_sel_hi:[1,0,1]
	s_nop 0
	v_pk_add_f32 v[20:21], v[20:21], v[66:67]
	ds_read_b128 v[86:89], v65 offset:32768
	s_waitcnt lgkmcnt(3)
	v_pk_mul_f32 v[76:77], v[80:81], v[90:91] op_sel:[0,1]
	s_nop 0
	v_pk_fma_f32 v[66:67], v[78:79], v[90:91], v[76:77] op_sel_hi:[1,0,1]
	s_nop 0
	v_pk_fma_f32 v[66:67], v[82:83], v[92:93], v[66:67] op_sel_hi:[1,0,1]
	v_mov_b32_e32 v92, v93
	v_pk_fma_f32 v[66:67], v[84:85], v[92:93], v[66:67] op_sel_hi:[1,0,1]
	s_nop 0
	v_pk_add_f32 v[22:23], v[22:23], v[66:67]
	ds_read_b128 v[90:93], v65 offset:36864
	s_waitcnt lgkmcnt(3)
	v_pk_mul_f32 v[76:77], v[80:81], v[100:101] op_sel:[0,1]
	s_nop 0
	v_pk_fma_f32 v[66:67], v[78:79], v[100:101], v[76:77] op_sel_hi:[1,0,1]
	s_nop 0
	v_pk_fma_f32 v[66:67], v[82:83], v[102:103], v[66:67] op_sel_hi:[1,0,1]
	v_mov_b32_e32 v102, v103
	v_pk_fma_f32 v[66:67], v[84:85], v[102:103], v[66:67] op_sel_hi:[1,0,1]
	s_nop 0
	v_pk_add_f32 v[24:25], v[24:25], v[66:67]
	ds_read_b128 v[100:103], v65 offset:40960
	s_waitcnt lgkmcnt(3)
	v_pk_mul_f32 v[76:77], v[80:81], v[104:105] op_sel:[0,1]
	s_nop 0
	v_pk_fma_f32 v[66:67], v[78:79], v[104:105], v[76:77] op_sel_hi:[1,0,1]
	s_nop 0
	v_pk_fma_f32 v[66:67], v[82:83], v[106:107], v[66:67] op_sel_hi:[1,0,1]
	v_mov_b32_e32 v106, v107
	v_pk_fma_f32 v[66:67], v[84:85], v[106:107], v[66:67] op_sel_hi:[1,0,1]
	s_nop 0
	v_pk_add_f32 v[26:27], v[26:27], v[66:67]
	ds_read_b128 v[104:107], v65 offset:45056
	s_waitcnt lgkmcnt(3)
	v_pk_mul_f32 v[76:77], v[80:81], v[86:87] op_sel:[0,1]
	s_nop 0
	v_pk_fma_f32 v[66:67], v[78:79], v[86:87], v[76:77] op_sel_hi:[1,0,1]
	s_nop 0
	v_pk_fma_f32 v[66:67], v[82:83], v[88:89], v[66:67] op_sel_hi:[1,0,1]
	v_mov_b32_e32 v88, v89
	v_pk_fma_f32 v[66:67], v[84:85], v[88:89], v[66:67] op_sel_hi:[1,0,1]
	s_nop 0
	v_pk_add_f32 v[28:29], v[28:29], v[66:67]
	ds_read_b128 v[86:89], v65 offset:49152
	s_waitcnt lgkmcnt(3)
	v_pk_mul_f32 v[76:77], v[80:81], v[90:91] op_sel:[0,1]
	s_nop 0
	v_pk_fma_f32 v[66:67], v[78:79], v[90:91], v[76:77] op_sel_hi:[1,0,1]
	s_nop 0
	v_pk_fma_f32 v[66:67], v[82:83], v[92:93], v[66:67] op_sel_hi:[1,0,1]
	v_mov_b32_e32 v92, v93
	v_pk_fma_f32 v[66:67], v[84:85], v[92:93], v[66:67] op_sel_hi:[1,0,1]
	s_nop 0
	v_pk_add_f32 v[30:31], v[30:31], v[66:67]
	ds_read_b128 v[90:93], v65 offset:53248
	s_waitcnt lgkmcnt(3)
	v_pk_mul_f32 v[76:77], v[80:81], v[100:101] op_sel:[0,1]
	s_nop 0
	v_pk_fma_f32 v[66:67], v[78:79], v[100:101], v[76:77] op_sel_hi:[1,0,1]
	s_nop 0
	v_pk_fma_f32 v[66:67], v[82:83], v[102:103], v[66:67] op_sel_hi:[1,0,1]
	v_mov_b32_e32 v102, v103
	v_pk_fma_f32 v[66:67], v[84:85], v[102:103], v[66:67] op_sel_hi:[1,0,1]
	s_nop 0
	v_pk_add_f32 v[32:33], v[32:33], v[66:67]
	ds_read_b128 v[100:103], v65 offset:57344
	s_waitcnt lgkmcnt(3)
	v_pk_mul_f32 v[76:77], v[80:81], v[104:105] op_sel:[0,1]
	s_nop 0
	v_pk_fma_f32 v[66:67], v[78:79], v[104:105], v[76:77] op_sel_hi:[1,0,1]
	s_nop 0
	v_pk_fma_f32 v[66:67], v[82:83], v[106:107], v[66:67] op_sel_hi:[1,0,1]
	v_mov_b32_e32 v106, v107
	v_pk_fma_f32 v[66:67], v[84:85], v[106:107], v[66:67] op_sel_hi:[1,0,1]
	s_nop 0
	v_pk_add_f32 v[34:35], v[34:35], v[66:67]
	ds_read_b128 v[104:107], v65 offset:61440
	s_waitcnt lgkmcnt(3)
	v_pk_mul_f32 v[76:77], v[80:81], v[86:87] op_sel:[0,1]
	s_nop 0
	v_pk_fma_f32 v[66:67], v[78:79], v[86:87], v[76:77] op_sel_hi:[1,0,1]
	s_nop 0
	v_pk_fma_f32 v[66:67], v[82:83], v[88:89], v[66:67] op_sel_hi:[1,0,1]
	v_mov_b32_e32 v88, v89
	v_pk_fma_f32 v[66:67], v[84:85], v[88:89], v[66:67] op_sel_hi:[1,0,1]
	s_nop 0
	v_pk_add_f32 v[36:37], v[36:37], v[66:67]
	ds_read_b128 v[86:89], v98
	s_waitcnt lgkmcnt(3)
	v_pk_mul_f32 v[76:77], v[80:81], v[90:91] op_sel:[0,1]
	s_nop 0
	v_pk_fma_f32 v[66:67], v[78:79], v[90:91], v[76:77] op_sel_hi:[1,0,1]
	s_nop 0
	v_pk_fma_f32 v[66:67], v[82:83], v[92:93], v[66:67] op_sel_hi:[1,0,1]
	v_mov_b32_e32 v92, v93
	v_pk_fma_f32 v[66:67], v[84:85], v[92:93], v[66:67] op_sel_hi:[1,0,1]
	s_nop 0
	v_pk_add_f32 v[38:39], v[38:39], v[66:67]
	ds_read_b128 v[90:93], v98 offset:4096
	s_waitcnt lgkmcnt(3)
	v_pk_mul_f32 v[76:77], v[80:81], v[100:101] op_sel:[0,1]
	s_nop 0
	v_pk_fma_f32 v[66:67], v[78:79], v[100:101], v[76:77] op_sel_hi:[1,0,1]
	s_nop 0
	v_pk_fma_f32 v[66:67], v[82:83], v[102:103], v[66:67] op_sel_hi:[1,0,1]
	v_mov_b32_e32 v102, v103
	v_pk_fma_f32 v[66:67], v[84:85], v[102:103], v[66:67] op_sel_hi:[1,0,1]
	s_nop 0
	v_pk_add_f32 v[40:41], v[40:41], v[66:67]
	ds_read_b128 v[100:103], v98 offset:8192
	s_waitcnt lgkmcnt(3)
	v_pk_mul_f32 v[76:77], v[80:81], v[104:105] op_sel:[0,1]
	s_nop 0
	v_pk_fma_f32 v[66:67], v[78:79], v[104:105], v[76:77] op_sel_hi:[1,0,1]
	s_nop 0
	v_pk_fma_f32 v[66:67], v[82:83], v[106:107], v[66:67] op_sel_hi:[1,0,1]
	v_mov_b32_e32 v106, v107
	v_pk_fma_f32 v[66:67], v[84:85], v[106:107], v[66:67] op_sel_hi:[1,0,1]
	s_nop 0
	v_pk_add_f32 v[42:43], v[42:43], v[66:67]
	ds_read_b128 v[104:107], v98 offset:12288
	s_waitcnt lgkmcnt(3)
	v_pk_mul_f32 v[76:77], v[80:81], v[86:87] op_sel:[0,1]
	s_nop 0
	v_pk_fma_f32 v[66:67], v[78:79], v[86:87], v[76:77] op_sel_hi:[1,0,1]
	s_nop 0
	v_pk_fma_f32 v[66:67], v[82:83], v[88:89], v[66:67] op_sel_hi:[1,0,1]
	v_mov_b32_e32 v88, v89
	v_pk_fma_f32 v[66:67], v[84:85], v[88:89], v[66:67] op_sel_hi:[1,0,1]
	s_nop 0
	v_pk_add_f32 v[44:45], v[44:45], v[66:67]
	ds_read_b128 v[86:89], v98 offset:16384
	s_waitcnt lgkmcnt(3)
; #define LAS __attribute__((address_space(3)))
; DI void phase_prep(ArgsP AP, LAS unsigned char* lds) {
;     ...
;             for (int k4 = 0; k4 < 32; ++k4) {
;                 f32x2 wv[4];
; #pragma unroll
;                 for (int kk = 0; kk < 4; ++kk) wv[kk] = *(const f32x2*)(wp + (size_t)(k4 * 4 + kk) * 6144);
; #pragma unroll
;                 for (int b = 0; b < 24; ++b) {
;                     const f32x4 cv = *(const LAS f32x4*)(cs + b * 1024 + wave * 128 + k4 * 4);
;                     acc[b][0] += cv[0] * wv[0][0] + cv[1] * wv[1][0] + cv[2] * wv[2][0] + cv[3] * wv[3][0];
;                     acc[b][1] += cv[0] * wv[0][1] + cv[1] * wv[1][1] + cv[2] * wv[2][1] + cv[3] * wv[3][1];
;                 }
;             }
	v_pk_mul_f32 v[76:77], v[80:81], v[90:91] op_sel:[0,1]
	s_nop 0
	v_pk_fma_f32 v[66:67], v[78:79], v[90:91], v[76:77] op_sel_hi:[1,0,1]
	s_nop 0
	v_pk_fma_f32 v[66:67], v[82:83], v[92:93], v[66:67] op_sel_hi:[1,0,1]
	v_mov_b32_e32 v92, v93
	v_pk_fma_f32 v[66:67], v[84:85], v[92:93], v[66:67] op_sel_hi:[1,0,1]
	s_nop 0
	v_pk_add_f32 v[46:47], v[46:47], v[66:67]
	ds_read_b128 v[90:93], v98 offset:20480
	s_waitcnt lgkmcnt(3)
	v_pk_mul_f32 v[76:77], v[80:81], v[100:101] op_sel:[0,1]
	s_nop 0
	v_pk_fma_f32 v[66:67], v[78:79], v[100:101], v[76:77] op_sel_hi:[1,0,1]
	s_nop 0
	v_pk_fma_f32 v[66:67], v[82:83], v[102:103], v[66:67] op_sel_hi:[1,0,1]
	v_mov_b32_e32 v102, v103
	v_pk_fma_f32 v[66:67], v[84:85], v[102:103], v[66:67] op_sel_hi:[1,0,1]
	s_nop 0
	v_pk_add_f32 v[48:49], v[48:49], v[66:67]
	ds_read_b128 v[100:103], v98 offset:24576
	s_waitcnt lgkmcnt(3)
	v_pk_mul_f32 v[76:77], v[80:81], v[104:105] op_sel:[0,1]
	s_nop 0
	v_pk_fma_f32 v[66:67], v[78:79], v[104:105], v[76:77] op_sel_hi:[1,0,1]
	s_nop 0
	v_pk_fma_f32 v[66:67], v[82:83], v[106:107], v[66:67] op_sel_hi:[1,0,1]
	v_mov_b32_e32 v106, v107
	v_pk_fma_f32 v[66:67], v[84:85], v[106:107], v[66:67] op_sel_hi:[1,0,1]
	s_nop 0
	v_pk_add_f32 v[50:51], v[50:51], v[66:67]
	ds_read_b128 v[104:107], v98 offset:28672
	s_waitcnt lgkmcnt(3)
	v_pk_mul_f32 v[76:77], v[80:81], v[86:87] op_sel:[0,1]
	s_nop 0
	v_pk_fma_f32 v[66:67], v[78:79], v[86:87], v[76:77] op_sel_hi:[1,0,1]
	s_nop 0
	v_pk_fma_f32 v[66:67], v[82:83], v[88:89], v[66:67] op_sel_hi:[1,0,1]
	v_mov_b32_e32 v88, v89
	v_pk_fma_f32 v[66:67], v[84:85], v[88:89], v[66:67] op_sel_hi:[1,0,1]
	s_nop 0
	v_pk_add_f32 v[52:53], v[52:53], v[66:67]
	s_waitcnt lgkmcnt(2)
	v_pk_mul_f32 v[76:77], v[80:81], v[90:91] op_sel:[0,1]
	s_nop 0
	v_pk_fma_f32 v[66:67], v[78:79], v[90:91], v[76:77] op_sel_hi:[1,0,1]
	s_nop 0
	v_pk_fma_f32 v[66:67], v[82:83], v[92:93], v[66:67] op_sel_hi:[1,0,1]
	v_mov_b32_e32 v92, v93
	v_pk_fma_f32 v[66:67], v[84:85], v[92:93], v[66:67] op_sel_hi:[1,0,1]
	s_nop 0
	v_pk_add_f32 v[54:55], v[54:55], v[66:67]
	s_waitcnt lgkmcnt(1)
	v_pk_mul_f32 v[76:77], v[80:81], v[100:101] op_sel:[0,1]
	s_nop 0
	v_pk_fma_f32 v[66:67], v[78:79], v[100:101], v[76:77] op_sel_hi:[1,0,1]
	s_nop 0
	v_pk_fma_f32 v[66:67], v[82:83], v[102:103], v[66:67] op_sel_hi:[1,0,1]
	v_mov_b32_e32 v102, v103
	v_pk_fma_f32 v[66:67], v[84:85], v[102:103], v[66:67] op_sel_hi:[1,0,1]
	s_nop 0
	v_pk_add_f32 v[56:57], v[56:57], v[66:67]
	s_waitcnt lgkmcnt(0)
	v_pk_mul_f32 v[76:77], v[80:81], v[104:105] op_sel:[0,1]
	s_nop 0
	v_pk_fma_f32 v[66:67], v[78:79], v[104:105], v[76:77] op_sel_hi:[1,0,1]
	s_nop 0
	v_pk_fma_f32 v[66:67], v[82:83], v[106:107], v[66:67] op_sel_hi:[1,0,1]
	v_mov_b32_e32 v106, v107
	v_pk_fma_f32 v[66:67], v[84:85], v[106:107], v[66:67] op_sel_hi:[1,0,1]
	s_nop 0
	v_pk_add_f32 v[58:59], v[58:59], v[66:67]
	s_waitcnt vmcnt(4)
	v_mov_b64_e32 v[78:79], v[108:109]
	v_mov_b64_e32 v[80:81], v[110:111]
	v_mov_b64_e32 v[82:83], v[112:113]
	v_mov_b64_e32 v[84:85], v[114:115]
	s_add_i32 s3, s16, s2
	s_add_i32 s6, s3, 0x10000
	v_mov_b32_e32 v65, s3
	v_mov_b32_e32 v98, s6
	s_add_i32 s2, s2, 16
	s_cmpk_lt_u32 s2, 0x1f0
	s_cselect_b32 s18, 0x18000, 0
	s_mov_b32 s19, 0
	v_lshl_add_u64 v[12:13], v[12:13], 0, s[18:19]
	ds_read_b128 v[86:89], v65
	ds_read_b128 v[90:93], v65 offset:4096
	ds_read_b128 v[100:103], v65 offset:8192
	s_mov_b32 s3, 0xfffee000
	v_add_co_u32_e32 v108, vcc, s3, v12
	s_mov_b32 s3, 0xffff4000
	s_nop 0
	v_addc_co_u32_e32 v109, vcc, -1, v13, vcc
	v_add_co_u32_e32 v66, vcc, s3, v12
	global_load_dwordx2 v[108:109], v[108:109], off
	s_nop 0
	v_addc_co_u32_e32 v67, vcc, -1, v13, vcc
	global_load_dwordx2 v[110:111], v[66:67], off
	s_movk_i32 s3, 0xa000
	v_add_co_u32_e32 v66, vcc, s3, v12
	s_nop 1
	v_addc_co_u32_e32 v67, vcc, -1, v13, vcc
	global_load_dwordx2 v[112:113], v[66:67], off
	global_load_dwordx2 v[114:115], v[12:13], off
	ds_read_b128 v[104:107], v65 offset:12288
	s_waitcnt lgkmcnt(3)
	v_pk_mul_f32 v[76:77], v[80:81], v[86:87] op_sel:[0,1]
	s_nop 0
	v_pk_fma_f32 v[66:67], v[78:79], v[86:87], v[76:77] op_sel_hi:[1,0,1]
	s_nop 0
	v_pk_fma_f32 v[66:67], v[82:83], v[88:89], v[66:67] op_sel_hi:[1,0,1]
	v_mov_b32_e32 v88, v89
	v_pk_fma_f32 v[66:67], v[84:85], v[88:89], v[66:67] op_sel_hi:[1,0,1]
	s_nop 0
	v_pk_add_f32 v[10:11], v[10:11], v[66:67]
	ds_read_b128 v[86:89], v65 offset:16384
	s_waitcnt lgkmcnt(3)
	v_pk_mul_f32 v[76:77], v[80:81], v[90:91] op_sel:[0,1]
	s_nop 0
	v_pk_fma_f32 v[66:67], v[78:79], v[90:91], v[76:77] op_sel_hi:[1,0,1]
	s_nop 0
	v_pk_fma_f32 v[66:67], v[82:83], v[92:93], v[66:67] op_sel_hi:[1,0,1]
	v_mov_b32_e32 v92, v93
	v_pk_fma_f32 v[66:67], v[84:85], v[92:93], v[66:67] op_sel_hi:[1,0,1]
	s_nop 0
	v_pk_add_f32 v[14:15], v[14:15], v[66:67]
	ds_read_b128 v[90:93], v65 offset:20480
	s_waitcnt lgkmcnt(3)
	v_pk_mul_f32 v[76:77], v[80:81], v[100:101] op_sel:[0,1]
	s_nop 0
	v_pk_fma_f32 v[66:67], v[78:79], v[100:101], v[76:77] op_sel_hi:[1,0,1]
	s_nop 0
	v_pk_fma_f32 v[66:67], v[82:83], v[102:103], v[66:67] op_sel_hi:[1,0,1]
	v_mov_b32_e32 v102, v103
	v_pk_fma_f32 v[66:67], v[84:85], v[102:103], v[66:67] op_sel_hi:[1,0,1]
	s_nop 0
	v_pk_add_f32 v[16:17], v[16:17], v[66:67]
	ds_read_b128 v[100:103], v65 offset:24576
	s_waitcnt lgkmcnt(3)
	v_pk_mul_f32 v[76:77], v[80:81], v[104:105] op_sel:[0,1]
	s_nop 0
	v_pk_fma_f32 v[66:67], v[78:79], v[104:105], v[76:77] op_sel_hi:[1,0,1]
	s_nop 0
	v_pk_fma_f32 v[66:67], v[82:83], v[106:107], v[66:67] op_sel_hi:[1,0,1]
	v_mov_b32_e32 v106, v107
	v_pk_fma_f32 v[66:67], v[84:85], v[106:107], v[66:67] op_sel_hi:[1,0,1]
	s_nop 0
	v_pk_add_f32 v[18:19], v[18:19], v[66:67]
	ds_read_b128 v[104:107], v65 offset:28672
	s_waitcnt lgkmcnt(3)
; #define LAS __attribute__((address_space(3)))
; DI void phase_prep(ArgsP AP, LAS unsigned char* lds) {
;     ...
;                 for (int b = 0; b < 24; ++b) {
;                     const f32x4 cv = *(const LAS f32x4*)(cs + b * 1024 + wave * 128 + k4 * 4);
;                     acc[b][0] += cv[0] * wv[0][0] + cv[1] * wv[1][0] + cv[2] * wv[2][0] + cv[3] * wv[3][0];
;                     acc[b][1] += cv[0] * wv[0][1] + cv[1] * wv[1][1] + cv[2] * wv[2][1] + cv[3] * wv[3][1];
;                 }
	v_pk_mul_f32 v[76:77], v[80:81], v[86:87] op_sel:[0,1]
	s_nop 0
	v_pk_fma_f32 v[66:67], v[78:79], v[86:87], v[76:77] op_sel_hi:[1,0,1]
	s_nop 0
	v_pk_fma_f32 v[66:67], v[82:83], v[88:89], v[66:67] op_sel_hi:[1,0,1]
	v_mov_b32_e32 v88, v89
	v_pk_fma_f32 v[66:67], v[84:85], v[88:89], v[66:67] op_sel_hi:[1,0,1]
	s_nop 0
	v_pk_add_f32 v[20:21], v[20:21], v[66:67]
	ds_read_b128 v[86:89], v65 offset:32768
	s_waitcnt lgkmcnt(3)
	v_pk_mul_f32 v[76:77], v[80:81], v[90:91] op_sel:[0,1]
	s_nop 0
	v_pk_fma_f32 v[66:67], v[78:79], v[90:91], v[76:77] op_sel_hi:[1,0,1]
	s_nop 0
	v_pk_fma_f32 v[66:67], v[82:83], v[92:93], v[66:67] op_sel_hi:[1,0,1]
	v_mov_b32_e32 v92, v93
	v_pk_fma_f32 v[66:67], v[84:85], v[92:93], v[66:67] op_sel_hi:[1,0,1]
	s_nop 0
	v_pk_add_f32 v[22:23], v[22:23], v[66:67]
	ds_read_b128 v[90:93], v65 offset:36864
	s_waitcnt lgkmcnt(3)
	v_pk_mul_f32 v[76:77], v[80:81], v[100:101] op_sel:[0,1]
	s_nop 0
	v_pk_fma_f32 v[66:67], v[78:79], v[100:101], v[76:77] op_sel_hi:[1,0,1]
	s_nop 0
	v_pk_fma_f32 v[66:67], v[82:83], v[102:103], v[66:67] op_sel_hi:[1,0,1]
	v_mov_b32_e32 v102, v103
	v_pk_fma_f32 v[66:67], v[84:85], v[102:103], v[66:67] op_sel_hi:[1,0,1]
	s_nop 0
	v_pk_add_f32 v[24:25], v[24:25], v[66:67]
	ds_read_b128 v[100:103], v65 offset:40960
	s_waitcnt lgkmcnt(3)
	v_pk_mul_f32 v[76:77], v[80:81], v[104:105] op_sel:[0,1]
	s_nop 0
	v_pk_fma_f32 v[66:67], v[78:79], v[104:105], v[76:77] op_sel_hi:[1,0,1]
	s_nop 0
	v_pk_fma_f32 v[66:67], v[82:83], v[106:107], v[66:67] op_sel_hi:[1,0,1]
	v_mov_b32_e32 v106, v107
	v_pk_fma_f32 v[66:67], v[84:85], v[106:107], v[66:67] op_sel_hi:[1,0,1]
	s_nop 0
	v_pk_add_f32 v[26:27], v[26:27], v[66:67]
	ds_read_b128 v[104:107], v65 offset:45056
	s_waitcnt lgkmcnt(3)
	v_pk_mul_f32 v[76:77], v[80:81], v[86:87] op_sel:[0,1]
	s_nop 0
	v_pk_fma_f32 v[66:67], v[78:79], v[86:87], v[76:77] op_sel_hi:[1,0,1]
	s_nop 0
	v_pk_fma_f32 v[66:67], v[82:83], v[88:89], v[66:67] op_sel_hi:[1,0,1]
	v_mov_b32_e32 v88, v89
	v_pk_fma_f32 v[66:67], v[84:85], v[88:89], v[66:67] op_sel_hi:[1,0,1]
	s_nop 0
	v_pk_add_f32 v[28:29], v[28:29], v[66:67]
	ds_read_b128 v[86:89], v65 offset:49152
	s_waitcnt lgkmcnt(3)
	v_pk_mul_f32 v[76:77], v[80:81], v[90:91] op_sel:[0,1]
	s_nop 0
	v_pk_fma_f32 v[66:67], v[78:79], v[90:91], v[76:77] op_sel_hi:[1,0,1]
	s_nop 0
	v_pk_fma_f32 v[66:67], v[82:83], v[92:93], v[66:67] op_sel_hi:[1,0,1]
	v_mov_b32_e32 v92, v93
	v_pk_fma_f32 v[66:67], v[84:85], v[92:93], v[66:67] op_sel_hi:[1,0,1]
	s_nop 0
	v_pk_add_f32 v[30:31], v[30:31], v[66:67]
	ds_read_b128 v[90:93], v65 offset:53248
	s_waitcnt lgkmcnt(3)
	v_pk_mul_f32 v[76:77], v[80:81], v[100:101] op_sel:[0,1]
	s_nop 0
	v_pk_fma_f32 v[66:67], v[78:79], v[100:101], v[76:77] op_sel_hi:[1,0,1]
	s_nop 0
	v_pk_fma_f32 v[66:67], v[82:83], v[102:103], v[66:67] op_sel_hi:[1,0,1]
	v_mov_b32_e32 v102, v103
	v_pk_fma_f32 v[66:67], v[84:85], v[102:103], v[66:67] op_sel_hi:[1,0,1]
	s_nop 0
	v_pk_add_f32 v[32:33], v[32:33], v[66:67]
	ds_read_b128 v[100:103], v65 offset:57344
	s_waitcnt lgkmcnt(3)
	v_pk_mul_f32 v[76:77], v[80:81], v[104:105] op_sel:[0,1]
	s_nop 0
	v_pk_fma_f32 v[66:67], v[78:79], v[104:105], v[76:77] op_sel_hi:[1,0,1]
	s_nop 0
	v_pk_fma_f32 v[66:67], v[82:83], v[106:107], v[66:67] op_sel_hi:[1,0,1]
	v_mov_b32_e32 v106, v107
	v_pk_fma_f32 v[66:67], v[84:85], v[106:107], v[66:67] op_sel_hi:[1,0,1]
	s_nop 0
	v_pk_add_f32 v[34:35], v[34:35], v[66:67]
	ds_read_b128 v[104:107], v65 offset:61440
	s_waitcnt lgkmcnt(3)
	v_pk_mul_f32 v[76:77], v[80:81], v[86:87] op_sel:[0,1]
	s_nop 0
	v_pk_fma_f32 v[66:67], v[78:79], v[86:87], v[76:77] op_sel_hi:[1,0,1]
	s_nop 0
	v_pk_fma_f32 v[66:67], v[82:83], v[88:89], v[66:67] op_sel_hi:[1,0,1]
	v_mov_b32_e32 v88, v89
	v_pk_fma_f32 v[66:67], v[84:85], v[88:89], v[66:67] op_sel_hi:[1,0,1]
	s_nop 0
	v_pk_add_f32 v[36:37], v[36:37], v[66:67]
	ds_read_b128 v[86:89], v98
	s_waitcnt lgkmcnt(3)
	v_pk_mul_f32 v[76:77], v[80:81], v[90:91] op_sel:[0,1]
	s_nop 0
	v_pk_fma_f32 v[66:67], v[78:79], v[90:91], v[76:77] op_sel_hi:[1,0,1]
	s_nop 0
	v_pk_fma_f32 v[66:67], v[82:83], v[92:93], v[66:67] op_sel_hi:[1,0,1]
	v_mov_b32_e32 v92, v93
	v_pk_fma_f32 v[66:67], v[84:85], v[92:93], v[66:67] op_sel_hi:[1,0,1]
	s_nop 0
	v_pk_add_f32 v[38:39], v[38:39], v[66:67]
	ds_read_b128 v[90:93], v98 offset:4096
	s_waitcnt lgkmcnt(3)
	v_pk_mul_f32 v[76:77], v[80:81], v[100:101] op_sel:[0,1]
	s_nop 0
	v_pk_fma_f32 v[66:67], v[78:79], v[100:101], v[76:77] op_sel_hi:[1,0,1]
	s_nop 0
	v_pk_fma_f32 v[66:67], v[82:83], v[102:103], v[66:67] op_sel_hi:[1,0,1]
	v_mov_b32_e32 v102, v103
	v_pk_fma_f32 v[66:67], v[84:85], v[102:103], v[66:67] op_sel_hi:[1,0,1]
	s_nop 0
	v_pk_add_f32 v[40:41], v[40:41], v[66:67]
	ds_read_b128 v[100:103], v98 offset:8192
	s_waitcnt lgkmcnt(3)
; #define LAS __attribute__((address_space(3)))
; DI void phase_prep(ArgsP AP, LAS unsigned char* lds) {
;     ...
;             for (int k4 = 0; k4 < 32; ++k4) {
;                 f32x2 wv[4];
; #pragma unroll
;                 for (int kk = 0; kk < 4; ++kk) wv[kk] = *(const f32x2*)(wp + (size_t)(k4 * 4 + kk) * 6144);
; #pragma unroll
;                 for (int b = 0; b < 24; ++b) {
;                     const f32x4 cv = *(const LAS f32x4*)(cs + b * 1024 + wave * 128 + k4 * 4);
;                     acc[b][0] += cv[0] * wv[0][0] + cv[1] * wv[1][0] + cv[2] * wv[2][0] + cv[3] * wv[3][0];
;                     acc[b][1] += cv[0] * wv[0][1] + cv[1] * wv[1][1] + cv[2] * wv[2][1] + cv[3] * wv[3][1];
;                 }
;             }
;             __syncthreads();
; #pragma unroll
;             for (int b = 0; b < 24; ++b) { cs[(wave * 24 + b) * 128 + 2 * lane] = acc[b][0]; cs[(wave * 24 + b) * 128 + 2 * lane + 1] = acc[b][1]; }
;             __syncthreads();
;             for (int o = tid; o < 24 * 128; o += 512) {
;                 const int b = o >> 7, c = o & 127; float sum = adab[l * 6144 + cgp * 128 + c];
; #pragma unroll
;                 for (int w = 0; w < 8; ++w) sum += cs[(w * 24 + b) * 128 + c];
	v_pk_mul_f32 v[76:77], v[80:81], v[104:105] op_sel:[0,1]
	s_nop 0
	v_pk_fma_f32 v[66:67], v[78:79], v[104:105], v[76:77] op_sel_hi:[1,0,1]
	s_nop 0
	v_pk_fma_f32 v[66:67], v[82:83], v[106:107], v[66:67] op_sel_hi:[1,0,1]
	v_mov_b32_e32 v106, v107
	v_pk_fma_f32 v[66:67], v[84:85], v[106:107], v[66:67] op_sel_hi:[1,0,1]
	s_nop 0
	v_pk_add_f32 v[42:43], v[42:43], v[66:67]
	ds_read_b128 v[104:107], v98 offset:12288
	s_waitcnt lgkmcnt(3)
	v_pk_mul_f32 v[76:77], v[80:81], v[86:87] op_sel:[0,1]
	s_nop 0
	v_pk_fma_f32 v[66:67], v[78:79], v[86:87], v[76:77] op_sel_hi:[1,0,1]
	s_nop 0
	v_pk_fma_f32 v[66:67], v[82:83], v[88:89], v[66:67] op_sel_hi:[1,0,1]
	v_mov_b32_e32 v88, v89
	v_pk_fma_f32 v[66:67], v[84:85], v[88:89], v[66:67] op_sel_hi:[1,0,1]
	s_nop 0
	v_pk_add_f32 v[44:45], v[44:45], v[66:67]
	ds_read_b128 v[86:89], v98 offset:16384
	s_waitcnt lgkmcnt(3)
	v_pk_mul_f32 v[76:77], v[80:81], v[90:91] op_sel:[0,1]
	s_nop 0
	v_pk_fma_f32 v[66:67], v[78:79], v[90:91], v[76:77] op_sel_hi:[1,0,1]
	s_nop 0
	v_pk_fma_f32 v[66:67], v[82:83], v[92:93], v[66:67] op_sel_hi:[1,0,1]
	v_mov_b32_e32 v92, v93
	v_pk_fma_f32 v[66:67], v[84:85], v[92:93], v[66:67] op_sel_hi:[1,0,1]
	s_nop 0
	v_pk_add_f32 v[46:47], v[46:47], v[66:67]
	ds_read_b128 v[90:93], v98 offset:20480
	s_waitcnt lgkmcnt(3)
	v_pk_mul_f32 v[76:77], v[80:81], v[100:101] op_sel:[0,1]
	s_nop 0
	v_pk_fma_f32 v[66:67], v[78:79], v[100:101], v[76:77] op_sel_hi:[1,0,1]
	s_nop 0
	v_pk_fma_f32 v[66:67], v[82:83], v[102:103], v[66:67] op_sel_hi:[1,0,1]
	v_mov_b32_e32 v102, v103
	v_pk_fma_f32 v[66:67], v[84:85], v[102:103], v[66:67] op_sel_hi:[1,0,1]
	s_nop 0
	v_pk_add_f32 v[48:49], v[48:49], v[66:67]
	ds_read_b128 v[100:103], v98 offset:24576
	s_waitcnt lgkmcnt(3)
	v_pk_mul_f32 v[76:77], v[80:81], v[104:105] op_sel:[0,1]
	s_nop 0
	v_pk_fma_f32 v[66:67], v[78:79], v[104:105], v[76:77] op_sel_hi:[1,0,1]
	s_nop 0
	v_pk_fma_f32 v[66:67], v[82:83], v[106:107], v[66:67] op_sel_hi:[1,0,1]
	v_mov_b32_e32 v106, v107
	v_pk_fma_f32 v[66:67], v[84:85], v[106:107], v[66:67] op_sel_hi:[1,0,1]
	s_nop 0
	v_pk_add_f32 v[50:51], v[50:51], v[66:67]
	ds_read_b128 v[104:107], v98 offset:28672
	s_waitcnt lgkmcnt(3)
	v_pk_mul_f32 v[76:77], v[80:81], v[86:87] op_sel:[0,1]
	s_nop 0
	v_pk_fma_f32 v[66:67], v[78:79], v[86:87], v[76:77] op_sel_hi:[1,0,1]
	s_nop 0
	v_pk_fma_f32 v[66:67], v[82:83], v[88:89], v[66:67] op_sel_hi:[1,0,1]
	v_mov_b32_e32 v88, v89
	v_pk_fma_f32 v[66:67], v[84:85], v[88:89], v[66:67] op_sel_hi:[1,0,1]
	s_nop 0
	v_pk_add_f32 v[52:53], v[52:53], v[66:67]
	s_waitcnt lgkmcnt(2)
	v_pk_mul_f32 v[76:77], v[80:81], v[90:91] op_sel:[0,1]
	s_nop 0
	v_pk_fma_f32 v[66:67], v[78:79], v[90:91], v[76:77] op_sel_hi:[1,0,1]
	s_nop 0
	v_pk_fma_f32 v[66:67], v[82:83], v[92:93], v[66:67] op_sel_hi:[1,0,1]
	v_mov_b32_e32 v92, v93
	v_pk_fma_f32 v[66:67], v[84:85], v[92:93], v[66:67] op_sel_hi:[1,0,1]
	s_nop 0
	v_pk_add_f32 v[54:55], v[54:55], v[66:67]
	s_waitcnt lgkmcnt(1)
	v_pk_mul_f32 v[76:77], v[80:81], v[100:101] op_sel:[0,1]
	s_nop 0
	v_pk_fma_f32 v[66:67], v[78:79], v[100:101], v[76:77] op_sel_hi:[1,0,1]
	s_nop 0
	v_pk_fma_f32 v[66:67], v[82:83], v[102:103], v[66:67] op_sel_hi:[1,0,1]
	v_mov_b32_e32 v102, v103
	v_pk_fma_f32 v[66:67], v[84:85], v[102:103], v[66:67] op_sel_hi:[1,0,1]
	s_nop 0
	v_pk_add_f32 v[56:57], v[56:57], v[66:67]
	s_waitcnt lgkmcnt(0)
	v_pk_mul_f32 v[76:77], v[80:81], v[104:105] op_sel:[0,1]
	s_nop 0
	v_pk_fma_f32 v[66:67], v[78:79], v[104:105], v[76:77] op_sel_hi:[1,0,1]
	s_nop 0
	v_pk_fma_f32 v[66:67], v[82:83], v[106:107], v[66:67] op_sel_hi:[1,0,1]
	v_mov_b32_e32 v106, v107
	v_pk_fma_f32 v[66:67], v[84:85], v[106:107], v[66:67] op_sel_hi:[1,0,1]
	s_nop 0
	v_pk_add_f32 v[58:59], v[58:59], v[66:67]
	s_cmpk_lg_i32 s2, 0x200
	s_cbranch_scc1 .LBB0_1166
	s_waitcnt vmcnt(0)
	s_barrier
	ds_write2st64_b64 v7, v[10:11], v[14:15] offset1:1
	ds_write2st64_b64 v7, v[16:17], v[18:19] offset0:2 offset1:3
	ds_write2st64_b64 v7, v[20:21], v[22:23] offset0:4 offset1:5
	ds_write2st64_b64 v7, v[24:25], v[26:27] offset0:6 offset1:7
	ds_write2st64_b64 v7, v[28:29], v[30:31] offset0:8 offset1:9
	ds_write2st64_b64 v7, v[32:33], v[34:35] offset0:10 offset1:11
	ds_write2st64_b64 v7, v[36:37], v[38:39] offset0:12 offset1:13
	ds_write2st64_b64 v7, v[40:41], v[42:43] offset0:14 offset1:15
	ds_write2st64_b64 v7, v[44:45], v[46:47] offset0:16 offset1:17
	ds_write2st64_b64 v7, v[48:49], v[50:51] offset0:18 offset1:19
	ds_write2st64_b64 v7, v[52:53], v[54:55] offset0:20 offset1:21
	ds_write2st64_b64 v7, v[56:57], v[58:59] offset0:22 offset1:23
	s_waitcnt lgkmcnt(0)
	s_barrier
	s_and_saveexec_b64 s[2:3], s[42:43]
	s_cbranch_execz .LBB0_1159
	s_mul_i32 s6, s14, 0x1800
	s_add_i32 s6, s6, s0
	v_or_b32_e32 v10, s6, v63
	v_ashrrev_i32_e32 v11, 31, v10
	s_mul_hi_i32 s15, s14, 24
	s_mul_i32 s14, s14, 24
	v_lshl_add_u64 v[10:11], v[10:11], 2, s[50:51]
	v_lshl_add_u64 v[12:13], s[0:1], 2, v[0:1]
	s_mov_b64 s[0:1], 0
	v_mov_b32_e32 v14, v2
